# branch projections: gated sum carried in the accumulators across the three z units (acc *= g_z/g_z+1 between units, no f32 M32 round trip through memory); f32 math
# speedup vs baseline: 1.0460x; 1.0460x over previous
; #define PG8_STAGE(bufoff, gbase, voff) do { _Pragma("unroll") for (int _i = 0; _i < 2; ++_i) \
;         __builtin_amdgcn_global_load_lds((const unsigned*)((const char*)(gbase) + (voff)[_i]), (LAS unsigned*)(lds + (bufoff) + ldsw + _i * 8192), 16, 0, 0); } while (0)
; #define PG8_LDA(dst, b, h) do { _Pragma("unroll") for (int m = 0; m < 4; ++m) _Pragma("unroll") for (int k = 0; k < 2; ++k) dst[m][k] = *(const LAS bf16x8*)(lds + PG8_SA(b, h) + aoff + m * 2048 + k * 1024); } while (0)
; #define PG8_LDB(dst, b, h) do { _Pragma("unroll") for (int n = 0; n < 2; ++n) _Pragma("unroll") for (int k = 0; k < 2; ++k) dst[n][k] = *(const LAS bf16x8*)(lds + PG8_SB(b, h) + boff + n * 2048 + k * 1024); } while (0)
; #define PG8_WAIT_V(n) asm volatile("s_waitcnt vmcnt(" #n ")" ::: "memory")
; #define PG8_WAIT_L(n) asm volatile("s_waitcnt lgkmcnt(" #n ")" ::: "memory")
; #define PG8_BAR __builtin_amdgcn_s_barrier()
; #define PG8_SCHED __builtin_amdgcn_sched_barrier(0)
; template <class Epi, bool ALIGN_EPI, bool ASLOT = false>
; __device__ __forceinline__ void gemm_phase(LAS unsigned char* lds, const Gemm g, const Sched& S, const Epi& E) {
;     ...
;     for (;;) {
;         const bool has_next = S.next(ui + 1, nxt);
;         const char* nA = has_next ? (const char*)g.A + (size_t)nxt.z * g.zA + (size_t)nxt.pm * pstepA : cA; const char* nB = has_next ? (const char*)g.Bt + (size_t)nxt.z * g.zB + (size_t)nxt.pn * tstep : cB;
;         for (int t = 0; t < nt; t += 2) {
;             const bool last = (t == nt - 2);
;             const char* a1 = cA + (size_t)(t + 1) * kstep;
;             const char* a2 = last ? nA : cA + (size_t)(t + 2) * kstep; const char* b2 = last ? nB : cB + (size_t)(t + 2) * kstep;
;             const char* a3 = a2 + kstep; const char* b3 = b2 + kstep;
;             PG8_LDB(B0, 0, 0); PG8_LDB(B1, 0, 1); PG8_SCHED; PG8_LDA(At, 0, 0); PG8_STAGE(PG8_SA(1, 1), a1 + hstep, voffA);
;             PG8_WAIT_V(8); PG8_WAIT_L(0); PG8_BAR; PG8_MMA(0, 0, At, B0); PG8_MMA(0, 1, At, B1); PG8_BAR; PG8_SCHED;
;     ...
;         for (int a = 0; a < 2; ++a)
; #pragma unroll
;             for (int b = 0; b < 2; ++b)
; #pragma unroll
;                 for (int m = 0; m < 4; ++m)
; #pragma unroll
;                     for (int n = 0; n < 2; ++n) acc[a][b][m][n] = (f32x4){0.f, 0.f, 0.f, 0.f};
.LBB0_663:
	s_mov_b32 s58, s57
	s_add_i32 s57, s57, 1
	s_cmp_lt_u32 s58, 2
	s_cselect_b64 s[22:23], -1, 0
	s_mov_b64 s[20:21], s[4:5]
	s_and_b64 s[4:5], s[22:23], exec
	v_readlane_b32 s4, v254, 21
	s_mov_b32 s3, s10
	s_mov_b32 s2, s8
	s_cselect_b32 s8, s57, s8
	s_cselect_b32 s10, s4, s10
	v_readlane_b32 s4, v254, 14
	s_mov_b32 s14, s12
	s_cselect_b32 s12, s4, s12
	s_ashr_i32 s9, s8, 31
	s_lshl_b64 s[4:5], s[8:9], 24
	v_readlane_b32 s11, v254, 8
	s_add_u32 s11, s11, s4
	v_readlane_b32 s4, v254, 9
	s_addc_u32 s15, s4, s5
	s_ashr_i32 s13, s12, 31
	s_lshl_b64 s[4:5], s[12:13], 18
	s_mov_b64 s[18:19], s[38:39]
	s_add_u32 s38, s11, s4
	s_addc_u32 s39, s15, s5
	s_and_b64 s[4:5], s[22:23], exec
	s_cselect_b32 s13, s39, s19
	s_cselect_b32 s15, s38, s18
	s_lshl_b64 s[4:5], s[8:9], 20
	s_add_u32 s9, s27, s4
	s_addc_u32 s24, s34, s5
	s_ashr_i32 s11, s10, 31
	s_lshl_b64 s[4:5], s[10:11], 18
	s_add_u32 s4, s9, s4
	s_addc_u32 s5, s24, s5
	s_and_b64 s[22:23], s[22:23], exec
	s_cselect_b32 s9, s5, s21
	s_cselect_b32 s11, s4, s20
	s_add_u32 s36, s18, 0x20080
	s_addc_u32 s37, s19, 0
	s_add_u32 s24, s20, 0x100
	s_addc_u32 s25, s21, 0
	s_mov_b32 s40, -2
	s_waitcnt vmcnt(0)
	s_cmp_lg_u32 s58, 0
	s_cbranch_scc1 .Lbr_keep_acc
	v_mov_b32_e32 v2, 0
	v_mov_b32_e32 v3, v2
	v_mov_b32_e32 v4, v2
	v_mov_b32_e32 v5, v2
	v_mov_b32_e32 v6, v2
	v_mov_b32_e32 v7, v2
	v_mov_b32_e32 v8, v2
	v_mov_b32_e32 v9, v2
	v_mov_b32_e32 v18, v2
	v_mov_b32_e32 v19, v2
	v_mov_b32_e32 v20, v2
	v_mov_b32_e32 v21, v2
	v_mov_b32_e32 v22, v2
	v_mov_b32_e32 v23, v2
	v_mov_b32_e32 v24, v2
	v_mov_b32_e32 v25, v2
	v_mov_b32_e32 v34, v2
	v_mov_b32_e32 v35, v2
	v_mov_b32_e32 v36, v2
	v_mov_b32_e32 v37, v2
	v_mov_b32_e32 v38, v2
	v_mov_b32_e32 v39, v2
	v_mov_b32_e32 v40, v2
	v_mov_b32_e32 v41, v2
	v_mov_b32_e32 v50, v2
	v_mov_b32_e32 v51, v2
	v_mov_b32_e32 v52, v2
	v_mov_b32_e32 v53, v2
	v_mov_b32_e32 v54, v2
	v_mov_b32_e32 v55, v2
	v_mov_b32_e32 v56, v2
	v_mov_b32_e32 v57, v2
	v_mov_b32_e32 v10, v2
	v_mov_b32_e32 v11, v2
	v_mov_b32_e32 v12, v2
	v_mov_b32_e32 v13, v2
	v_mov_b32_e32 v14, v2
	v_mov_b32_e32 v15, v2
	v_mov_b32_e32 v16, v2
	v_mov_b32_e32 v17, v2
	v_mov_b32_e32 v26, v2
	v_mov_b32_e32 v27, v2
	v_mov_b32_e32 v28, v2
	v_mov_b32_e32 v29, v2
	v_mov_b32_e32 v30, v2
	v_mov_b32_e32 v31, v2
	v_mov_b32_e32 v32, v2
	v_mov_b32_e32 v33, v2
	v_mov_b32_e32 v42, v2
	v_mov_b32_e32 v43, v2
	v_mov_b32_e32 v44, v2
	v_mov_b32_e32 v45, v2
	v_mov_b32_e32 v46, v2
	v_mov_b32_e32 v47, v2
	v_mov_b32_e32 v48, v2
	v_mov_b32_e32 v49, v2
	v_mov_b32_e32 v58, v2
	v_mov_b32_e32 v59, v2
	v_mov_b32_e32 v60, v2
	v_mov_b32_e32 v61, v2
	v_mov_b32_e32 v62, v2
	v_mov_b32_e32 v63, v2
	v_mov_b32_e32 v64, v2
	v_mov_b32_e32 v65, v2
	v_mov_b32_e32 v66, v2
	v_mov_b32_e32 v67, v2
	v_mov_b32_e32 v68, v2
	v_mov_b32_e32 v69, v2
	v_mov_b32_e32 v70, v2
	v_mov_b32_e32 v71, v2
	v_mov_b32_e32 v72, v2
	v_mov_b32_e32 v73, v2
	v_mov_b32_e32 v82, v2
	v_mov_b32_e32 v83, v2
	v_mov_b32_e32 v84, v2
	v_mov_b32_e32 v85, v2
	v_mov_b32_e32 v86, v2
	v_mov_b32_e32 v87, v2
	v_mov_b32_e32 v88, v2
	v_mov_b32_e32 v89, v2
	v_mov_b32_e32 v98, v2
	v_mov_b32_e32 v99, v2
	v_mov_b32_e32 v100, v2
	v_mov_b32_e32 v101, v2
	v_mov_b32_e32 v102, v2
	v_mov_b32_e32 v103, v2
	v_mov_b32_e32 v104, v2
	v_mov_b32_e32 v105, v2
	v_mov_b32_e32 v114, v2
	v_mov_b32_e32 v115, v2
	v_mov_b32_e32 v116, v2
	v_mov_b32_e32 v117, v2
	v_mov_b32_e32 v118, v2
	v_mov_b32_e32 v119, v2
	v_mov_b32_e32 v120, v2
	v_mov_b32_e32 v121, v2
	v_mov_b32_e32 v74, v2
	v_mov_b32_e32 v75, v2
	v_mov_b32_e32 v76, v2
	v_mov_b32_e32 v77, v2
	v_mov_b32_e32 v78, v2
	v_mov_b32_e32 v79, v2
	v_mov_b32_e32 v80, v2
	v_mov_b32_e32 v81, v2
	v_mov_b32_e32 v90, v2
	v_mov_b32_e32 v91, v2
	v_mov_b32_e32 v92, v2
	v_mov_b32_e32 v93, v2
	v_mov_b32_e32 v94, v2
	v_mov_b32_e32 v95, v2
	v_mov_b32_e32 v96, v2
	v_mov_b32_e32 v97, v2
	v_mov_b32_e32 v106, v2
	v_mov_b32_e32 v107, v2
	v_mov_b32_e32 v108, v2
	v_mov_b32_e32 v109, v2
	v_mov_b32_e32 v110, v2
	v_mov_b32_e32 v111, v2
	v_mov_b32_e32 v112, v2
	v_mov_b32_e32 v113, v2
	v_mov_b32_e32 v122, v2
	v_mov_b32_e32 v123, v2
	v_mov_b32_e32 v124, v2
	v_mov_b32_e32 v125, v2
	v_mov_b32_e32 v126, v2
	v_mov_b32_e32 v127, v2
	v_mov_b32_e32 v128, v2
	v_mov_b32_e32 v129, v2
.Lbr_keep_acc:
.LBB0_664:
	v_add_u32_e32 v148, s28, v151
	ds_read_b128 v[140:143], v148
	ds_read_b128 v[144:147], v148 offset:1024
	ds_read_b128 v[154:157], v148 offset:2048
	ds_read_b128 v[158:161], v148 offset:3072
	v_add_u32_e32 v148, s33, v151
	ds_read_b128 v[162:165], v148
	ds_read_b128 v[166:169], v148 offset:1024
	ds_read_b128 v[170:173], v148 offset:2048
	ds_read_b128 v[174:177], v148 offset:3072
	s_add_u32 s18, s36, 0xfffe0080
	s_addc_u32 s19, s37, -1
	s_cmp_eq_u32 s40, 4
	s_cselect_b32 s21, s13, s19
	s_cselect_b32 s20, s15, s18
	s_cselect_b32 s19, s9, s25
	s_cselect_b32 s18, s11, s24
	v_lshl_add_u64 v[148:149], s[36:37], 0, v[136:137]
	s_add_i32 m0, s51, 0xc000
	ds_read_b128 v[178:181], v153
	ds_read_b128 v[182:185], v153 offset:1024
	ds_read_b128 v[186:189], v153 offset:2048
	ds_read_b128 v[190:193], v153 offset:3072
	ds_read_b128 v[194:197], v153 offset:4096
	ds_read_b128 v[198:201], v153 offset:5120
	ds_read_b128 v[202:205], v153 offset:6144
	ds_read_b128 v[206:209], v153 offset:7168
	global_load_lds_dwordx4 v[148:149], off
	v_lshl_add_u64 v[148:149], s[36:37], 0, v[138:139]
	s_add_i32 m0, s51, 0xe000
	s_nop 0
	global_load_lds_dwordx4 v[148:149], off
	s_waitcnt vmcnt(8)
	s_waitcnt lgkmcnt(0)
	s_barrier
; #define PG8_STAGE(bufoff, gbase, voff) do { _Pragma("unroll") for (int _i = 0; _i < 2; ++_i) \
;         __builtin_amdgcn_global_load_lds((const unsigned*)((const char*)(gbase) + (voff)[_i]), (LAS unsigned*)(lds + (bufoff) + ldsw + _i * 8192), 16, 0, 0); } while (0)
; #define PG8_LDA(dst, b, h) do { _Pragma("unroll") for (int m = 0; m < 4; ++m) _Pragma("unroll") for (int k = 0; k < 2; ++k) dst[m][k] = *(const LAS bf16x8*)(lds + PG8_SA(b, h) + aoff + m * 2048 + k * 1024); } while (0)
; #define PG8_LDB(dst, b, h) do { _Pragma("unroll") for (int n = 0; n < 2; ++n) _Pragma("unroll") for (int k = 0; k < 2; ++k) dst[n][k] = *(const LAS bf16x8*)(lds + PG8_SB(b, h) + boff + n * 2048 + k * 1024); } while (0)
; #define PG8_MMA(ai, bj, At, Bt) do { __builtin_amdgcn_s_setprio(1); _Pragma("unroll") for (int m = 0; m < 4; ++m) _Pragma("unroll") for (int n = 0; n < 2; ++n) _Pragma("unroll") for (int k = 0; k < 2; ++k) \
;         acc[ai][bj][m][n] = __builtin_amdgcn_mfma_f32_16x16x32_bf16(Bt[n][k], At[m][k], acc[ai][bj][m][n], 0, 0, 0); __builtin_amdgcn_s_setprio(0); } while (0)
; #define PG8_WAIT_V(n) asm volatile("s_waitcnt vmcnt(" #n ")" ::: "memory")
; #define PG8_WAIT_L(n) asm volatile("s_waitcnt lgkmcnt(" #n ")" ::: "memory")
; #define PG8_BAR __builtin_amdgcn_s_barrier()
; #define PG8_SCHED __builtin_amdgcn_sched_barrier(0)
; template <class Epi, bool ALIGN_EPI, bool ASLOT = false>
; __device__ __forceinline__ void gemm_phase(LAS unsigned char* lds, const Gemm g, const Sched& S, const Epi& E) {
;     ...
;             PG8_LDB(B0, 0, 0); PG8_LDB(B1, 0, 1); PG8_SCHED; PG8_LDA(At, 0, 0); PG8_STAGE(PG8_SA(1, 1), a1 + hstep, voffA);
;             PG8_WAIT_V(8); PG8_WAIT_L(0); PG8_BAR; PG8_MMA(0, 0, At, B0); PG8_MMA(0, 1, At, B1); PG8_BAR; PG8_SCHED;
;             PG8_LDA(At, 0, 1); PG8_STAGE(PG8_SB(0, 0), b2, voffB); PG8_STAGE(PG8_SB(0, 1), b2 + hstep, voffB); PG8_STAGE(PG8_SA(0, 0), a2, voffA);
;             PG8_WAIT_V(8); PG8_WAIT_L(0); PG8_BAR; PG8_MMA(1, 0, At, B0); PG8_MMA(1, 1, At, B1); PG8_BAR; PG8_SCHED;
	s_setprio 1
	s_waitcnt lgkmcnt(0)
	v_mfma_f32_16x16x32_bf16 v[126:129], v[140:143], v[178:181], v[126:129]
	v_mfma_f32_16x16x32_bf16 v[122:125], v[154:157], v[178:181], v[122:125]
	v_mfma_f32_16x16x32_bf16 v[110:113], v[140:143], v[186:189], v[110:113]
	v_mfma_f32_16x16x32_bf16 v[106:109], v[154:157], v[186:189], v[106:109]
	v_mfma_f32_16x16x32_bf16 v[94:97], v[140:143], v[194:197], v[94:97]
	v_mfma_f32_16x16x32_bf16 v[90:93], v[154:157], v[194:197], v[90:93]
	v_mfma_f32_16x16x32_bf16 v[78:81], v[140:143], v[202:205], v[78:81]
	v_mfma_f32_16x16x32_bf16 v[74:77], v[154:157], v[202:205], v[74:77]
	v_mfma_f32_16x16x32_bf16 v[126:129], v[144:147], v[182:185], v[126:129]
	v_mfma_f32_16x16x32_bf16 v[122:125], v[158:161], v[182:185], v[122:125]
	v_mfma_f32_16x16x32_bf16 v[110:113], v[144:147], v[190:193], v[110:113]
	v_mfma_f32_16x16x32_bf16 v[106:109], v[158:161], v[190:193], v[106:109]
	v_mfma_f32_16x16x32_bf16 v[94:97], v[144:147], v[198:201], v[94:97]
	v_mfma_f32_16x16x32_bf16 v[90:93], v[158:161], v[198:201], v[90:93]
	v_mfma_f32_16x16x32_bf16 v[78:81], v[144:147], v[206:209], v[78:81]
	v_mfma_f32_16x16x32_bf16 v[74:77], v[158:161], v[206:209], v[74:77]
	s_setprio 0
	s_setprio 1
	v_mfma_f32_16x16x32_bf16 v[118:121], v[162:165], v[178:181], v[118:121]
	v_mfma_f32_16x16x32_bf16 v[114:117], v[170:173], v[178:181], v[114:117]
	v_mfma_f32_16x16x32_bf16 v[102:105], v[162:165], v[186:189], v[102:105]
	v_mfma_f32_16x16x32_bf16 v[98:101], v[170:173], v[186:189], v[98:101]
	v_mfma_f32_16x16x32_bf16 v[86:89], v[162:165], v[194:197], v[86:89]
	v_mfma_f32_16x16x32_bf16 v[82:85], v[170:173], v[194:197], v[82:85]
	v_mfma_f32_16x16x32_bf16 v[70:73], v[162:165], v[202:205], v[70:73]
	v_mfma_f32_16x16x32_bf16 v[66:69], v[170:173], v[202:205], v[66:69]
	v_mfma_f32_16x16x32_bf16 v[118:121], v[166:169], v[182:185], v[118:121]
	v_mfma_f32_16x16x32_bf16 v[114:117], v[174:177], v[182:185], v[114:117]
	v_mfma_f32_16x16x32_bf16 v[102:105], v[166:169], v[190:193], v[102:105]
	v_mfma_f32_16x16x32_bf16 v[98:101], v[174:177], v[190:193], v[98:101]
	v_mfma_f32_16x16x32_bf16 v[86:89], v[166:169], v[198:201], v[86:89]
	v_mfma_f32_16x16x32_bf16 v[82:85], v[174:177], v[198:201], v[82:85]
	v_mfma_f32_16x16x32_bf16 v[70:73], v[166:169], v[206:209], v[70:73]
	v_mfma_f32_16x16x32_bf16 v[66:69], v[174:177], v[206:209], v[66:69]
	s_setprio 0
	s_barrier
	s_add_i32 s22, s28, s50
	v_lshl_add_u64 v[148:149], s[18:19], 0, v[0:1]
	s_mov_b32 m0, s22
	ds_read_b128 v[178:181], v153 offset:16384
	ds_read_b128 v[182:185], v153 offset:17408
	ds_read_b128 v[186:189], v153 offset:18432
	ds_read_b128 v[190:193], v153 offset:19456
	ds_read_b128 v[194:197], v153 offset:20480
	ds_read_b128 v[198:201], v153 offset:21504
	ds_read_b128 v[202:205], v153 offset:22528
	ds_read_b128 v[206:209], v153 offset:23552
	global_load_lds_dwordx4 v[148:149], off
	s_add_i32 m0, s22, 0x2000
	s_add_u32 s22, s18, 0x20000
	v_lshl_add_u64 v[210:211], s[18:19], 0, v[134:135]
	s_addc_u32 s23, s19, 0
	s_add_i32 s30, s33, s50
	global_load_lds_dwordx4 v[210:211], off
	v_lshl_add_u64 v[212:213], s[22:23], 0, v[0:1]
	s_mov_b32 m0, s30
	v_lshl_add_u64 v[214:215], s[20:21], 0, v[132:133]
	global_load_lds_dwordx4 v[212:213], off
	v_lshl_add_u64 v[212:213], s[22:23], 0, v[134:135]
	s_add_i32 m0, s30, 0x2000
	s_nop 0
	global_load_lds_dwordx4 v[212:213], off
	v_lshl_add_u64 v[212:213], s[20:21], 0, v[130:131]
	s_mov_b32 m0, s51
	s_nop 0
	global_load_lds_dwordx4 v[212:213], off
	s_mov_b32 m0, s52
	s_nop 0
	global_load_lds_dwordx4 v[214:215], off
	s_waitcnt vmcnt(8)
	s_waitcnt lgkmcnt(0)
	s_barrier
	s_setprio 1
	s_waitcnt lgkmcnt(0)
	v_mfma_f32_16x16x32_bf16 v[62:65], v[140:143], v[178:181], v[62:65]
	v_mfma_f32_16x16x32_bf16 v[58:61], v[154:157], v[178:181], v[58:61]
	v_mfma_f32_16x16x32_bf16 v[46:49], v[140:143], v[186:189], v[46:49]
	v_mfma_f32_16x16x32_bf16 v[42:45], v[154:157], v[186:189], v[42:45]
	v_mfma_f32_16x16x32_bf16 v[30:33], v[140:143], v[194:197], v[30:33]
	v_mfma_f32_16x16x32_bf16 v[26:29], v[154:157], v[194:197], v[26:29]
	v_mfma_f32_16x16x32_bf16 v[14:17], v[140:143], v[202:205], v[14:17]
	v_mfma_f32_16x16x32_bf16 v[10:13], v[154:157], v[202:205], v[10:13]
	v_mfma_f32_16x16x32_bf16 v[62:65], v[144:147], v[182:185], v[62:65]
	v_mfma_f32_16x16x32_bf16 v[58:61], v[158:161], v[182:185], v[58:61]
	v_mfma_f32_16x16x32_bf16 v[46:49], v[144:147], v[190:193], v[46:49]
	v_mfma_f32_16x16x32_bf16 v[42:45], v[158:161], v[190:193], v[42:45]
	v_mfma_f32_16x16x32_bf16 v[30:33], v[144:147], v[198:201], v[30:33]
	v_mfma_f32_16x16x32_bf16 v[26:29], v[158:161], v[198:201], v[26:29]
	v_mfma_f32_16x16x32_bf16 v[14:17], v[144:147], v[206:209], v[14:17]
	v_mfma_f32_16x16x32_bf16 v[10:13], v[158:161], v[206:209], v[10:13]
	s_setprio 0
	s_setprio 1
	v_mfma_f32_16x16x32_bf16 v[54:57], v[162:165], v[178:181], v[54:57]
	v_mfma_f32_16x16x32_bf16 v[50:53], v[170:173], v[178:181], v[50:53]
	v_mfma_f32_16x16x32_bf16 v[38:41], v[162:165], v[186:189], v[38:41]
	v_mfma_f32_16x16x32_bf16 v[34:37], v[170:173], v[186:189], v[34:37]
	v_mfma_f32_16x16x32_bf16 v[22:25], v[162:165], v[194:197], v[22:25]
	v_mfma_f32_16x16x32_bf16 v[18:21], v[170:173], v[194:197], v[18:21]
	v_mfma_f32_16x16x32_bf16 v[6:9], v[162:165], v[202:205], v[6:9]
	v_mfma_f32_16x16x32_bf16 v[2:5], v[170:173], v[202:205], v[2:5]
	v_mfma_f32_16x16x32_bf16 v[54:57], v[166:169], v[182:185], v[54:57]
	v_mfma_f32_16x16x32_bf16 v[50:53], v[174:177], v[182:185], v[50:53]
	v_mfma_f32_16x16x32_bf16 v[38:41], v[166:169], v[190:193], v[38:41]
	v_mfma_f32_16x16x32_bf16 v[34:37], v[174:177], v[190:193], v[34:37]
	v_mfma_f32_16x16x32_bf16 v[22:25], v[166:169], v[198:201], v[22:25]
	v_mfma_f32_16x16x32_bf16 v[18:21], v[174:177], v[198:201], v[18:21]
	v_mfma_f32_16x16x32_bf16 v[6:9], v[166:169], v[206:209], v[6:9]
	v_mfma_f32_16x16x32_bf16 v[2:5], v[174:177], v[206:209], v[2:5]
	s_setprio 0
	s_barrier
; #define PG8_STAGE(bufoff, gbase, voff) do { _Pragma("unroll") for (int _i = 0; _i < 2; ++_i) \
;         __builtin_amdgcn_global_load_lds((const unsigned*)((const char*)(gbase) + (voff)[_i]), (LAS unsigned*)(lds + (bufoff) + ldsw + _i * 8192), 16, 0, 0); } while (0)
; #define PG8_LDA(dst, b, h) do { _Pragma("unroll") for (int m = 0; m < 4; ++m) _Pragma("unroll") for (int k = 0; k < 2; ++k) dst[m][k] = *(const LAS bf16x8*)(lds + PG8_SA(b, h) + aoff + m * 2048 + k * 1024); } while (0)
; #define PG8_LDB(dst, b, h) do { _Pragma("unroll") for (int n = 0; n < 2; ++n) _Pragma("unroll") for (int k = 0; k < 2; ++k) dst[n][k] = *(const LAS bf16x8*)(lds + PG8_SB(b, h) + boff + n * 2048 + k * 1024); } while (0)
; #define PG8_MMA(ai, bj, At, Bt) do { __builtin_amdgcn_s_setprio(1); _Pragma("unroll") for (int m = 0; m < 4; ++m) _Pragma("unroll") for (int n = 0; n < 2; ++n) _Pragma("unroll") for (int k = 0; k < 2; ++k) \
;         acc[ai][bj][m][n] = __builtin_amdgcn_mfma_f32_16x16x32_bf16(Bt[n][k], At[m][k], acc[ai][bj][m][n], 0, 0, 0); __builtin_amdgcn_s_setprio(0); } while (0)
; #define PG8_WAIT_V(n) asm volatile("s_waitcnt vmcnt(" #n ")" ::: "memory")
; #define PG8_WAIT_L(n) asm volatile("s_waitcnt lgkmcnt(" #n ")" ::: "memory")
; #define PG8_BAR __builtin_amdgcn_s_barrier()
; #define PG8_SCHED __builtin_amdgcn_sched_barrier(0)
; template <class Epi, bool ALIGN_EPI, bool ASLOT = false>
; __device__ __forceinline__ void gemm_phase(LAS unsigned char* lds, const Gemm g, const Sched& S, const Epi& E) {
;     ...
;             PG8_LDB(B0, 1, 0); PG8_LDB(B1, 1, 1); PG8_SCHED; PG8_LDA(At, 1, 0); PG8_STAGE(PG8_SA(0, 1), a2 + hstep, voffA);
;             PG8_WAIT_V(8); PG8_WAIT_L(0); PG8_BAR; PG8_MMA(0, 0, At, B0); PG8_MMA(0, 1, At, B1); PG8_BAR; PG8_SCHED;
;             PG8_LDA(At, 1, 1); PG8_STAGE(PG8_SB(1, 0), b3, voffB); PG8_STAGE(PG8_SB(1, 1), b3 + hstep, voffB); PG8_STAGE(PG8_SA(1, 0), a3, voffA);
;             PG8_WAIT_V(8); PG8_WAIT_L(0); PG8_BAR; PG8_MMA(1, 0, At, B0); PG8_MMA(1, 1, At, B1); PG8_BAR; PG8_SCHED;
	v_add_u32_e32 v158, s29, v151
	v_add_u32_e32 v174, s26, v151
	ds_read_b128 v[140:143], v158
	ds_read_b128 v[144:147], v158 offset:1024
	ds_read_b128 v[154:157], v158 offset:2048
	ds_read_b128 v[158:161], v158 offset:3072
	ds_read_b128 v[162:165], v174
	ds_read_b128 v[166:169], v174 offset:1024
	ds_read_b128 v[170:173], v174 offset:2048
	ds_read_b128 v[174:177], v174 offset:3072
	s_add_u32 s20, s20, 0x20000
	s_addc_u32 s21, s21, 0
	s_mov_b32 m0, s53
	v_lshl_add_u64 v[220:221], s[20:21], 0, v[130:131]
	ds_read_b128 v[178:181], v153 offset:32768
	ds_read_b128 v[182:185], v153 offset:33792
	ds_read_b128 v[186:189], v153 offset:34816
	ds_read_b128 v[190:193], v153 offset:35840
	ds_read_b128 v[194:197], v153 offset:36864
	ds_read_b128 v[198:201], v153 offset:37888
	ds_read_b128 v[202:205], v153 offset:38912
	ds_read_b128 v[206:209], v153 offset:39936
	global_load_lds_dwordx4 v[220:221], off
	v_lshl_add_u64 v[220:221], s[20:21], 0, v[132:133]
	s_mov_b32 m0, s54
	s_nop 0
	global_load_lds_dwordx4 v[220:221], off
	s_waitcnt vmcnt(8)
	s_waitcnt lgkmcnt(0)
	s_barrier
	s_setprio 1
	s_waitcnt lgkmcnt(0)
	v_mfma_f32_16x16x32_bf16 v[126:129], v[140:143], v[178:181], v[126:129]
	v_mfma_f32_16x16x32_bf16 v[122:125], v[154:157], v[178:181], v[122:125]
	v_mfma_f32_16x16x32_bf16 v[110:113], v[140:143], v[186:189], v[110:113]
	v_mfma_f32_16x16x32_bf16 v[106:109], v[154:157], v[186:189], v[106:109]
	v_mfma_f32_16x16x32_bf16 v[94:97], v[140:143], v[194:197], v[94:97]
	v_mfma_f32_16x16x32_bf16 v[90:93], v[154:157], v[194:197], v[90:93]
	v_mfma_f32_16x16x32_bf16 v[78:81], v[140:143], v[202:205], v[78:81]
	v_mfma_f32_16x16x32_bf16 v[74:77], v[154:157], v[202:205], v[74:77]
	v_mfma_f32_16x16x32_bf16 v[126:129], v[144:147], v[182:185], v[126:129]
	v_mfma_f32_16x16x32_bf16 v[122:125], v[158:161], v[182:185], v[122:125]
	v_mfma_f32_16x16x32_bf16 v[110:113], v[144:147], v[190:193], v[110:113]
	v_mfma_f32_16x16x32_bf16 v[106:109], v[158:161], v[190:193], v[106:109]
	v_mfma_f32_16x16x32_bf16 v[94:97], v[144:147], v[198:201], v[94:97]
	v_mfma_f32_16x16x32_bf16 v[90:93], v[158:161], v[198:201], v[90:93]
	v_mfma_f32_16x16x32_bf16 v[78:81], v[144:147], v[206:209], v[78:81]
	v_mfma_f32_16x16x32_bf16 v[74:77], v[158:161], v[206:209], v[74:77]
	s_setprio 0
	s_setprio 1
	v_mfma_f32_16x16x32_bf16 v[118:121], v[162:165], v[178:181], v[118:121]
	v_mfma_f32_16x16x32_bf16 v[114:117], v[170:173], v[178:181], v[114:117]
	v_mfma_f32_16x16x32_bf16 v[102:105], v[162:165], v[186:189], v[102:105]
	v_mfma_f32_16x16x32_bf16 v[98:101], v[170:173], v[186:189], v[98:101]
	v_mfma_f32_16x16x32_bf16 v[86:89], v[162:165], v[194:197], v[86:89]
	v_mfma_f32_16x16x32_bf16 v[82:85], v[170:173], v[194:197], v[82:85]
	v_mfma_f32_16x16x32_bf16 v[70:73], v[162:165], v[202:205], v[70:73]
	v_mfma_f32_16x16x32_bf16 v[66:69], v[170:173], v[202:205], v[66:69]
	v_mfma_f32_16x16x32_bf16 v[118:121], v[166:169], v[182:185], v[118:121]
	v_mfma_f32_16x16x32_bf16 v[114:117], v[174:177], v[182:185], v[114:117]
	v_mfma_f32_16x16x32_bf16 v[102:105], v[166:169], v[190:193], v[102:105]
	v_mfma_f32_16x16x32_bf16 v[98:101], v[174:177], v[190:193], v[98:101]
	v_mfma_f32_16x16x32_bf16 v[86:89], v[166:169], v[198:201], v[86:89]
	v_mfma_f32_16x16x32_bf16 v[82:85], v[174:177], v[198:201], v[82:85]
	v_mfma_f32_16x16x32_bf16 v[70:73], v[166:169], v[206:209], v[70:73]
	v_mfma_f32_16x16x32_bf16 v[66:69], v[174:177], v[206:209], v[66:69]
	s_setprio 0
	s_barrier
	s_add_i32 s20, s29, s50
	v_lshl_add_u64 v[148:149], v[148:149], 0, s[16:17]
	s_mov_b32 m0, s20
	ds_read_b128 v[178:181], v153 offset:49152
	ds_read_b128 v[182:185], v153 offset:50176
	ds_read_b128 v[186:189], v153 offset:51200
	ds_read_b128 v[190:193], v153 offset:52224
	ds_read_b128 v[194:197], v153 offset:53248
	ds_read_b128 v[198:201], v153 offset:54272
	ds_read_b128 v[202:205], v153 offset:55296
	ds_read_b128 v[206:209], v153 offset:56320
	global_load_lds_dwordx4 v[148:149], off
	s_add_i32 m0, s20, 0x2000
	s_add_u32 s18, s18, 0x20080
	v_lshl_add_u64 v[148:149], v[210:211], 0, s[16:17]
	s_addc_u32 s19, s19, 0
	s_add_i32 s20, s26, s50
	global_load_lds_dwordx4 v[148:149], off
	v_lshl_add_u64 v[148:149], s[18:19], 0, v[0:1]
	s_mov_b32 m0, s20
	s_nop 0
	global_load_lds_dwordx4 v[148:149], off
	v_lshl_add_u64 v[148:149], s[18:19], 0, v[134:135]
	s_add_i32 m0, s20, 0x2000
	s_nop 0
	global_load_lds_dwordx4 v[148:149], off
	v_lshl_add_u64 v[148:149], v[212:213], 0, s[16:17]
	s_mov_b32 m0, s55
	s_nop 0
	global_load_lds_dwordx4 v[148:149], off
	v_lshl_add_u64 v[148:149], v[214:215], 0, s[16:17]
	s_mov_b32 m0, s56
	s_nop 0
	global_load_lds_dwordx4 v[148:149], off
	s_waitcnt vmcnt(8)
	s_waitcnt lgkmcnt(0)
	s_barrier
; __device__ __forceinline__ float bf_lo(unsigned w) { return __uint_as_float(w << 16); }
; __device__ __forceinline__ float bf_hi(unsigned w) { return __uint_as_float(w & 0xffff0000u); }
; #define PG8_STAGE(bufoff, gbase, voff) do { _Pragma("unroll") for (int _i = 0; _i < 2; ++_i) \
;         __builtin_amdgcn_global_load_lds((const unsigned*)((const char*)(gbase) + (voff)[_i]), (LAS unsigned*)(lds + (bufoff) + ldsw + _i * 8192), 16, 0, 0); } while (0)
; #define PG8_LDA(dst, b, h) do { _Pragma("unroll") for (int m = 0; m < 4; ++m) _Pragma("unroll") for (int k = 0; k < 2; ++k) dst[m][k] = *(const LAS bf16x8*)(lds + PG8_SA(b, h) + aoff + m * 2048 + k * 1024); } while (0)
; #define PG8_WAIT_V(n) asm volatile("s_waitcnt vmcnt(" #n ")" ::: "memory")
; #define PG8_WAIT_L(n) asm volatile("s_waitcnt lgkmcnt(" #n ")" ::: "memory")
; #define PG8_BAR __builtin_amdgcn_s_barrier()
; #define PG8_SCHED __builtin_amdgcn_sched_barrier(0)
;     __device__ __forceinline__ void operator()(ACC_T, const Unit& u, int wr, int wc, int fr, int fq) const {
;     ...
;             for (int m = 0; m < 4; ++m) { const size_t row = (size_t)(row0 + ai * HALF + m * 16);
; #pragma unroll
;                 for (int bj = 0; bj < 2; ++bj) {
;                     const u32x4 gw = *(const u32x4*)(Gt + row * GW + u.z * DM + col0 + bj * HALF);
;                     f32x4 v0 = acc[ai][bj][m][0], v1 = acc[ai][bj][m][1];
;                     v0[0] *= bf_lo(gw.x); v0[1] *= bf_hi(gw.x); v0[2] *= bf_lo(gw.y); v0[3] *= bf_hi(gw.y);
;                     v1[0] *= bf_lo(gw.z); v1[1] *= bf_hi(gw.z); v1[2] *= bf_lo(gw.w); v1[3] *= bf_hi(gw.w);
; template <class Epi, bool ALIGN_EPI, bool ASLOT = false>
; __device__ __forceinline__ void gemm_phase(LAS unsigned char* lds, const Gemm g, const Sched& S, const Epi& E) {
;     ...
;             PG8_WAIT_V(8); PG8_WAIT_L(0); PG8_BAR; PG8_MMA(0, 0, At, B0); PG8_MMA(0, 1, At, B1); PG8_BAR; PG8_SCHED;
;             PG8_LDA(At, 1, 1); PG8_STAGE(PG8_SB(1, 0), b3, voffB); PG8_STAGE(PG8_SB(1, 1), b3 + hstep, voffB); PG8_STAGE(PG8_SA(1, 0), a3, voffA);
;             PG8_WAIT_V(8); PG8_WAIT_L(0); PG8_BAR; PG8_MMA(1, 0, At, B0); PG8_MMA(1, 1, At, B1); PG8_BAR; PG8_SCHED;
;         }
;         if constexpr (ALIGN_EPI) { if (wr == 0) PG8_BAR; }
;         E(acc, cur, wr, wc, fr, fq);
;         if (!has_next) break;
	s_setprio 1
	s_waitcnt lgkmcnt(0)
	v_mfma_f32_16x16x32_bf16 v[62:65], v[140:143], v[178:181], v[62:65]
	v_mfma_f32_16x16x32_bf16 v[58:61], v[154:157], v[178:181], v[58:61]
	v_mfma_f32_16x16x32_bf16 v[46:49], v[140:143], v[186:189], v[46:49]
	v_mfma_f32_16x16x32_bf16 v[42:45], v[154:157], v[186:189], v[42:45]
	v_mfma_f32_16x16x32_bf16 v[30:33], v[140:143], v[194:197], v[30:33]
	v_mfma_f32_16x16x32_bf16 v[26:29], v[154:157], v[194:197], v[26:29]
	v_mfma_f32_16x16x32_bf16 v[14:17], v[140:143], v[202:205], v[14:17]
	v_mfma_f32_16x16x32_bf16 v[10:13], v[154:157], v[202:205], v[10:13]
	v_mfma_f32_16x16x32_bf16 v[62:65], v[144:147], v[182:185], v[62:65]
	v_mfma_f32_16x16x32_bf16 v[58:61], v[158:161], v[182:185], v[58:61]
	v_mfma_f32_16x16x32_bf16 v[46:49], v[144:147], v[190:193], v[46:49]
	v_mfma_f32_16x16x32_bf16 v[42:45], v[158:161], v[190:193], v[42:45]
	v_mfma_f32_16x16x32_bf16 v[30:33], v[144:147], v[198:201], v[30:33]
	v_mfma_f32_16x16x32_bf16 v[26:29], v[158:161], v[198:201], v[26:29]
	v_mfma_f32_16x16x32_bf16 v[14:17], v[144:147], v[206:209], v[14:17]
	v_mfma_f32_16x16x32_bf16 v[10:13], v[158:161], v[206:209], v[10:13]
	s_setprio 0
	s_setprio 1
	v_mfma_f32_16x16x32_bf16 v[54:57], v[162:165], v[178:181], v[54:57]
	v_mfma_f32_16x16x32_bf16 v[50:53], v[170:173], v[178:181], v[50:53]
	v_mfma_f32_16x16x32_bf16 v[38:41], v[162:165], v[186:189], v[38:41]
	v_mfma_f32_16x16x32_bf16 v[34:37], v[170:173], v[186:189], v[34:37]
	v_mfma_f32_16x16x32_bf16 v[22:25], v[162:165], v[194:197], v[22:25]
	v_mfma_f32_16x16x32_bf16 v[18:21], v[170:173], v[194:197], v[18:21]
	v_mfma_f32_16x16x32_bf16 v[6:9], v[162:165], v[202:205], v[6:9]
	v_mfma_f32_16x16x32_bf16 v[2:5], v[170:173], v[202:205], v[2:5]
	v_mfma_f32_16x16x32_bf16 v[54:57], v[166:169], v[182:185], v[54:57]
	v_mfma_f32_16x16x32_bf16 v[50:53], v[174:177], v[182:185], v[50:53]
	v_mfma_f32_16x16x32_bf16 v[38:41], v[166:169], v[190:193], v[38:41]
	v_mfma_f32_16x16x32_bf16 v[34:37], v[174:177], v[190:193], v[34:37]
	v_mfma_f32_16x16x32_bf16 v[22:25], v[166:169], v[198:201], v[22:25]
	v_mfma_f32_16x16x32_bf16 v[18:21], v[174:177], v[198:201], v[18:21]
	v_mfma_f32_16x16x32_bf16 v[6:9], v[166:169], v[206:209], v[6:9]
	v_mfma_f32_16x16x32_bf16 v[2:5], v[174:177], v[206:209], v[2:5]
	s_setprio 0
	s_barrier
	s_add_i32 s40, s40, 2
	s_add_u32 s36, s36, 0x100
	s_addc_u32 s37, s37, 0
	s_add_u32 s24, s24, 0x100
	s_addc_u32 s25, s25, 0
	s_cmp_gt_u32 s40, 5
	s_cbranch_scc0 .LBB0_664
	s_and_b64 vcc, exec, s[6:7]
	s_cbranch_vccz .LBB0_667
	s_barrier
.LBB0_667:
	v_readlane_b32 s24, v251, 58
	v_readlane_b32 s25, v251, 59
	v_readlane_b32 s22, v254, 52
	v_readlane_b32 s23, v254, 53
	v_lshl_or_b32 v143, s3, 8, v152
	v_mul_u32_u24_e32 v140, 0x1800, v150
	v_lshlrev_b32_e32 v142, 11, v150
	v_lshl_add_u32 v140, v143, 1, v140
	v_lshl_add_u32 v142, v143, 1, v142
	s_mul_i32 s44, s14, 0x180000
	s_lshl_b32 s45, s2, 11
	s_add_u32 s44, s44, s45
	s_add_u32 s24, s24, s44
	s_addc_u32 s25, s25, 0
	s_lshl_b32 s44, s14, 19
	s_add_u32 s22, s22, s44
	s_addc_u32 s23, s23, 0
	s_cmp_eq_u32 s2, 2
	s_cbranch_scc1 .Lbr_zlast
	global_load_dwordx4 v[144:147], v140, s[24:25]
	global_load_dwordx4 v[154:157], v140, s[24:25] offset:2048
	global_load_dwordx4 v[158:161], v140, s[24:25] offset:256
	global_load_dwordx4 v[162:165], v140, s[24:25] offset:2304
	s_add_u32 s24, s24, 0x18000
	s_addc_u32 s25, s25, 0
	global_load_dwordx4 v[166:169], v140, s[24:25]
	global_load_dwordx4 v[170:173], v140, s[24:25] offset:2048
	global_load_dwordx4 v[174:177], v140, s[24:25] offset:256
	global_load_dwordx4 v[178:181], v140, s[24:25] offset:2304
	s_add_u32 s24, s24, 0x18000
	s_addc_u32 s25, s25, 0
	global_load_dwordx4 v[182:185], v140, s[24:25]
	global_load_dwordx4 v[186:189], v140, s[24:25] offset:2048
	global_load_dwordx4 v[190:193], v140, s[24:25] offset:256
	global_load_dwordx4 v[194:197], v140, s[24:25] offset:2304
	s_add_u32 s24, s24, 0x18000
	s_addc_u32 s25, s25, 0
	global_load_dwordx4 v[198:201], v140, s[24:25]
	global_load_dwordx4 v[202:205], v140, s[24:25] offset:2048
	s_waitcnt vmcnt(12)
	v_lshlrev_b32_e32 v148, 16, v144
	v_and_b32_e32 v149, 0xffff0000, v144
	v_lshlrev_b32_e32 v210, 16, v146
	v_and_b32_e32 v211, 0xffff0000, v146
	v_lshlrev_b32_e32 v144, 16, v145
	v_and_b32_e32 v145, 0xffff0000, v145
	v_lshlrev_b32_e32 v146, 16, v147
	v_and_b32_e32 v147, 0xffff0000, v147
	v_lshlrev_b32_e32 v212, 16, v154
	v_and_b32_e32 v213, 0xffff0000, v154
	v_lshlrev_b32_e32 v214, 16, v156
	v_and_b32_e32 v215, 0xffff0000, v156
	v_lshlrev_b32_e32 v154, 16, v155
	v_and_b32_e32 v155, 0xffff0000, v155
	v_lshlrev_b32_e32 v156, 16, v157
	v_and_b32_e32 v157, 0xffff0000, v157
	v_rcp_f32_e32 v212, v212
	v_rcp_f32_e32 v213, v213
	v_rcp_f32_e32 v154, v154
	v_rcp_f32_e32 v155, v155
	v_rcp_f32_e32 v214, v214
	v_rcp_f32_e32 v215, v215
	v_rcp_f32_e32 v156, v156
	v_rcp_f32_e32 v157, v157
	s_nop 0
	v_pk_mul_f32 v[148:149], v[148:149], v[212:213]
	v_pk_mul_f32 v[144:145], v[144:145], v[154:155]
	v_pk_mul_f32 v[210:211], v[210:211], v[214:215]
	v_pk_mul_f32 v[146:147], v[146:147], v[156:157]
	v_pk_mul_f32 v[126:127], v[126:127], v[148:149]
	v_pk_mul_f32 v[128:129], v[128:129], v[144:145]
	v_pk_mul_f32 v[122:123], v[122:123], v[210:211]
	v_pk_mul_f32 v[124:125], v[124:125], v[146:147]
	global_load_dwordx4 v[206:209], v140, s[24:25] offset:256
	global_load_dwordx4 v[144:147], v140, s[24:25] offset:2304
	s_add_u32 s24, s24, 0x78000
	s_addc_u32 s25, s25, 0
	s_waitcnt vmcnt(12)
; __device__ __forceinline__ float bf_lo(unsigned w) { return __uint_as_float(w << 16); }
; __device__ __forceinline__ float bf_hi(unsigned w) { return __uint_as_float(w & 0xffff0000u); }
;     __device__ __forceinline__ void operator()(ACC_T, const Unit& u, int wr, int wc, int fr, int fq) const {
;     ...
;             for (int m = 0; m < 4; ++m) { const size_t row = (size_t)(row0 + ai * HALF + m * 16);
; #pragma unroll
;                 for (int bj = 0; bj < 2; ++bj) {
;                     const u32x4 gw = *(const u32x4*)(Gt + row * GW + u.z * DM + col0 + bj * HALF);
;                     f32x4 v0 = acc[ai][bj][m][0], v1 = acc[ai][bj][m][1];
;                     v0[0] *= bf_lo(gw.x); v0[1] *= bf_hi(gw.x); v0[2] *= bf_lo(gw.y); v0[3] *= bf_hi(gw.y);
;                     v1[0] *= bf_lo(gw.z); v1[1] *= bf_hi(gw.z); v1[2] *= bf_lo(gw.w); v1[3] *= bf_hi(gw.w);
	v_lshlrev_b32_e32 v148, 16, v158
	v_and_b32_e32 v149, 0xffff0000, v158
	v_lshlrev_b32_e32 v210, 16, v160
	v_and_b32_e32 v211, 0xffff0000, v160
	v_lshlrev_b32_e32 v158, 16, v159
	v_and_b32_e32 v159, 0xffff0000, v159
	v_lshlrev_b32_e32 v160, 16, v161
	v_and_b32_e32 v161, 0xffff0000, v161
	v_lshlrev_b32_e32 v212, 16, v162
	v_and_b32_e32 v213, 0xffff0000, v162
	v_lshlrev_b32_e32 v214, 16, v164
	v_and_b32_e32 v215, 0xffff0000, v164
	v_lshlrev_b32_e32 v162, 16, v163
	v_and_b32_e32 v163, 0xffff0000, v163
	v_lshlrev_b32_e32 v164, 16, v165
	v_and_b32_e32 v165, 0xffff0000, v165
	v_rcp_f32_e32 v212, v212
	v_rcp_f32_e32 v213, v213
	v_rcp_f32_e32 v162, v162
	v_rcp_f32_e32 v163, v163
	v_rcp_f32_e32 v214, v214
	v_rcp_f32_e32 v215, v215
	v_rcp_f32_e32 v164, v164
	v_rcp_f32_e32 v165, v165
	s_nop 0
	v_pk_mul_f32 v[148:149], v[148:149], v[212:213]
	v_pk_mul_f32 v[158:159], v[158:159], v[162:163]
	v_pk_mul_f32 v[210:211], v[210:211], v[214:215]
	v_pk_mul_f32 v[160:161], v[160:161], v[164:165]
	v_pk_mul_f32 v[118:119], v[118:119], v[148:149]
	v_pk_mul_f32 v[120:121], v[120:121], v[158:159]
	v_pk_mul_f32 v[114:115], v[114:115], v[210:211]
	v_pk_mul_f32 v[116:117], v[116:117], v[160:161]
	global_load_dwordx4 v[154:157], v140, s[24:25]
	global_load_dwordx4 v[158:161], v140, s[24:25] offset:2048
	s_waitcnt vmcnt(12)
	v_lshlrev_b32_e32 v148, 16, v166
	v_and_b32_e32 v149, 0xffff0000, v166
	v_lshlrev_b32_e32 v210, 16, v168
	v_and_b32_e32 v211, 0xffff0000, v168
	v_lshlrev_b32_e32 v166, 16, v167
	v_and_b32_e32 v167, 0xffff0000, v167
	v_lshlrev_b32_e32 v168, 16, v169
	v_and_b32_e32 v169, 0xffff0000, v169
	v_lshlrev_b32_e32 v212, 16, v170
	v_and_b32_e32 v213, 0xffff0000, v170
	v_lshlrev_b32_e32 v214, 16, v172
	v_and_b32_e32 v215, 0xffff0000, v172
	v_lshlrev_b32_e32 v170, 16, v171
	v_and_b32_e32 v171, 0xffff0000, v171
	v_lshlrev_b32_e32 v172, 16, v173
	v_and_b32_e32 v173, 0xffff0000, v173
	v_rcp_f32_e32 v212, v212
	v_rcp_f32_e32 v213, v213
	v_rcp_f32_e32 v170, v170
	v_rcp_f32_e32 v171, v171
	v_rcp_f32_e32 v214, v214
	v_rcp_f32_e32 v215, v215
	v_rcp_f32_e32 v172, v172
	v_rcp_f32_e32 v173, v173
	s_nop 0
	v_pk_mul_f32 v[148:149], v[148:149], v[212:213]
	v_pk_mul_f32 v[166:167], v[166:167], v[170:171]
	v_pk_mul_f32 v[210:211], v[210:211], v[214:215]
	v_pk_mul_f32 v[168:169], v[168:169], v[172:173]
	v_pk_mul_f32 v[110:111], v[110:111], v[148:149]
	v_pk_mul_f32 v[112:113], v[112:113], v[166:167]
	v_pk_mul_f32 v[106:107], v[106:107], v[210:211]
	v_pk_mul_f32 v[108:109], v[108:109], v[168:169]
	global_load_dwordx4 v[162:165], v140, s[24:25] offset:256
	global_load_dwordx4 v[166:169], v140, s[24:25] offset:2304
	s_add_u32 s24, s24, 0x18000
	s_addc_u32 s25, s25, 0
	s_waitcnt vmcnt(12)
	v_lshlrev_b32_e32 v148, 16, v174
	v_and_b32_e32 v149, 0xffff0000, v174
	v_lshlrev_b32_e32 v210, 16, v176
	v_and_b32_e32 v211, 0xffff0000, v176
	v_lshlrev_b32_e32 v174, 16, v175
	v_and_b32_e32 v175, 0xffff0000, v175
	v_lshlrev_b32_e32 v176, 16, v177
	v_and_b32_e32 v177, 0xffff0000, v177
	v_lshlrev_b32_e32 v212, 16, v178
	v_and_b32_e32 v213, 0xffff0000, v178
	v_lshlrev_b32_e32 v214, 16, v180
	v_and_b32_e32 v215, 0xffff0000, v180
	v_lshlrev_b32_e32 v178, 16, v179
	v_and_b32_e32 v179, 0xffff0000, v179
	v_lshlrev_b32_e32 v180, 16, v181
	v_and_b32_e32 v181, 0xffff0000, v181
	v_rcp_f32_e32 v212, v212
	v_rcp_f32_e32 v213, v213
	v_rcp_f32_e32 v178, v178
	v_rcp_f32_e32 v179, v179
	v_rcp_f32_e32 v214, v214
	v_rcp_f32_e32 v215, v215
	v_rcp_f32_e32 v180, v180
	v_rcp_f32_e32 v181, v181
	s_nop 0
	v_pk_mul_f32 v[148:149], v[148:149], v[212:213]
	v_pk_mul_f32 v[174:175], v[174:175], v[178:179]
	v_pk_mul_f32 v[210:211], v[210:211], v[214:215]
	v_pk_mul_f32 v[176:177], v[176:177], v[180:181]
	v_pk_mul_f32 v[102:103], v[102:103], v[148:149]
	v_pk_mul_f32 v[104:105], v[104:105], v[174:175]
	v_pk_mul_f32 v[98:99], v[98:99], v[210:211]
	v_pk_mul_f32 v[100:101], v[100:101], v[176:177]
	global_load_dwordx4 v[170:173], v140, s[24:25]
	global_load_dwordx4 v[174:177], v140, s[24:25] offset:2048
	s_waitcnt vmcnt(12)
	v_lshlrev_b32_e32 v148, 16, v182
	v_and_b32_e32 v149, 0xffff0000, v182
	v_lshlrev_b32_e32 v210, 16, v184
	v_and_b32_e32 v211, 0xffff0000, v184
	v_lshlrev_b32_e32 v182, 16, v183
	v_and_b32_e32 v183, 0xffff0000, v183
	v_lshlrev_b32_e32 v184, 16, v185
	v_and_b32_e32 v185, 0xffff0000, v185
	v_lshlrev_b32_e32 v212, 16, v186
	v_and_b32_e32 v213, 0xffff0000, v186
	v_lshlrev_b32_e32 v214, 16, v188
	v_and_b32_e32 v215, 0xffff0000, v188
	v_lshlrev_b32_e32 v186, 16, v187
	v_and_b32_e32 v187, 0xffff0000, v187
	v_lshlrev_b32_e32 v188, 16, v189
	v_and_b32_e32 v189, 0xffff0000, v189
	v_rcp_f32_e32 v212, v212
	v_rcp_f32_e32 v213, v213
	v_rcp_f32_e32 v186, v186
	v_rcp_f32_e32 v187, v187
	v_rcp_f32_e32 v214, v214
	v_rcp_f32_e32 v215, v215
	v_rcp_f32_e32 v188, v188
	v_rcp_f32_e32 v189, v189
	s_nop 0
	v_pk_mul_f32 v[148:149], v[148:149], v[212:213]
	v_pk_mul_f32 v[182:183], v[182:183], v[186:187]
	v_pk_mul_f32 v[210:211], v[210:211], v[214:215]
	v_pk_mul_f32 v[184:185], v[184:185], v[188:189]
	v_pk_mul_f32 v[94:95], v[94:95], v[148:149]
	v_pk_mul_f32 v[96:97], v[96:97], v[182:183]
	v_pk_mul_f32 v[90:91], v[90:91], v[210:211]
	v_pk_mul_f32 v[92:93], v[92:93], v[184:185]
	global_load_dwordx4 v[178:181], v140, s[24:25] offset:256
	global_load_dwordx4 v[182:185], v140, s[24:25] offset:2304
	s_add_u32 s24, s24, 0x18000
	s_addc_u32 s25, s25, 0
	s_waitcnt vmcnt(12)
; __device__ __forceinline__ float bf_lo(unsigned w) { return __uint_as_float(w << 16); }
; __device__ __forceinline__ float bf_hi(unsigned w) { return __uint_as_float(w & 0xffff0000u); }
;     __device__ __forceinline__ void operator()(ACC_T, const Unit& u, int wr, int wc, int fr, int fq) const {
;     ...
;             for (int m = 0; m < 4; ++m) { const size_t row = (size_t)(row0 + ai * HALF + m * 16);
; #pragma unroll
;                 for (int bj = 0; bj < 2; ++bj) {
;                     const u32x4 gw = *(const u32x4*)(Gt + row * GW + u.z * DM + col0 + bj * HALF);
;                     f32x4 v0 = acc[ai][bj][m][0], v1 = acc[ai][bj][m][1];
;                     v0[0] *= bf_lo(gw.x); v0[1] *= bf_hi(gw.x); v0[2] *= bf_lo(gw.y); v0[3] *= bf_hi(gw.y);
;                     v1[0] *= bf_lo(gw.z); v1[1] *= bf_hi(gw.z); v1[2] *= bf_lo(gw.w); v1[3] *= bf_hi(gw.w);
	v_lshlrev_b32_e32 v148, 16, v190
	v_and_b32_e32 v149, 0xffff0000, v190
	v_lshlrev_b32_e32 v210, 16, v192
	v_and_b32_e32 v211, 0xffff0000, v192
	v_lshlrev_b32_e32 v190, 16, v191
	v_and_b32_e32 v191, 0xffff0000, v191
	v_lshlrev_b32_e32 v192, 16, v193
	v_and_b32_e32 v193, 0xffff0000, v193
	v_lshlrev_b32_e32 v212, 16, v194
	v_and_b32_e32 v213, 0xffff0000, v194
	v_lshlrev_b32_e32 v214, 16, v196
	v_and_b32_e32 v215, 0xffff0000, v196
	v_lshlrev_b32_e32 v194, 16, v195
	v_and_b32_e32 v195, 0xffff0000, v195
	v_lshlrev_b32_e32 v196, 16, v197
	v_and_b32_e32 v197, 0xffff0000, v197
	v_rcp_f32_e32 v212, v212
	v_rcp_f32_e32 v213, v213
	v_rcp_f32_e32 v194, v194
	v_rcp_f32_e32 v195, v195
	v_rcp_f32_e32 v214, v214
	v_rcp_f32_e32 v215, v215
	v_rcp_f32_e32 v196, v196
	v_rcp_f32_e32 v197, v197
	s_nop 0
	v_pk_mul_f32 v[148:149], v[148:149], v[212:213]
	v_pk_mul_f32 v[190:191], v[190:191], v[194:195]
	v_pk_mul_f32 v[210:211], v[210:211], v[214:215]
	v_pk_mul_f32 v[192:193], v[192:193], v[196:197]
	v_pk_mul_f32 v[86:87], v[86:87], v[148:149]
	v_pk_mul_f32 v[88:89], v[88:89], v[190:191]
	v_pk_mul_f32 v[82:83], v[82:83], v[210:211]
	v_pk_mul_f32 v[84:85], v[84:85], v[192:193]
	global_load_dwordx4 v[186:189], v140, s[24:25]
	global_load_dwordx4 v[190:193], v140, s[24:25] offset:2048
	s_waitcnt vmcnt(12)
	v_lshlrev_b32_e32 v148, 16, v198
	v_and_b32_e32 v149, 0xffff0000, v198
	v_lshlrev_b32_e32 v210, 16, v200
	v_and_b32_e32 v211, 0xffff0000, v200
	v_lshlrev_b32_e32 v198, 16, v199
	v_and_b32_e32 v199, 0xffff0000, v199
	v_lshlrev_b32_e32 v200, 16, v201
	v_and_b32_e32 v201, 0xffff0000, v201
	v_lshlrev_b32_e32 v212, 16, v202
	v_and_b32_e32 v213, 0xffff0000, v202
	v_lshlrev_b32_e32 v214, 16, v204
	v_and_b32_e32 v215, 0xffff0000, v204
	v_lshlrev_b32_e32 v202, 16, v203
	v_and_b32_e32 v203, 0xffff0000, v203
	v_lshlrev_b32_e32 v204, 16, v205
	v_and_b32_e32 v205, 0xffff0000, v205
	v_rcp_f32_e32 v212, v212
	v_rcp_f32_e32 v213, v213
	v_rcp_f32_e32 v202, v202
	v_rcp_f32_e32 v203, v203
	v_rcp_f32_e32 v214, v214
	v_rcp_f32_e32 v215, v215
	v_rcp_f32_e32 v204, v204
	v_rcp_f32_e32 v205, v205
	s_nop 0
	v_pk_mul_f32 v[148:149], v[148:149], v[212:213]
	v_pk_mul_f32 v[198:199], v[198:199], v[202:203]
	v_pk_mul_f32 v[210:211], v[210:211], v[214:215]
	v_pk_mul_f32 v[200:201], v[200:201], v[204:205]
	v_pk_mul_f32 v[78:79], v[78:79], v[148:149]
	v_pk_mul_f32 v[80:81], v[80:81], v[198:199]
	v_pk_mul_f32 v[74:75], v[74:75], v[210:211]
	v_pk_mul_f32 v[76:77], v[76:77], v[200:201]
	global_load_dwordx4 v[194:197], v140, s[24:25] offset:256
	global_load_dwordx4 v[198:201], v140, s[24:25] offset:2304
	s_add_u32 s24, s24, 0x18000
	s_addc_u32 s25, s25, 0
	s_waitcnt vmcnt(12)
	v_lshlrev_b32_e32 v148, 16, v206
	v_and_b32_e32 v149, 0xffff0000, v206
	v_lshlrev_b32_e32 v210, 16, v208
	v_and_b32_e32 v211, 0xffff0000, v208
	v_lshlrev_b32_e32 v206, 16, v207
	v_and_b32_e32 v207, 0xffff0000, v207
	v_lshlrev_b32_e32 v208, 16, v209
	v_and_b32_e32 v209, 0xffff0000, v209
	v_lshlrev_b32_e32 v212, 16, v144
	v_and_b32_e32 v213, 0xffff0000, v144
	v_lshlrev_b32_e32 v214, 16, v146
	v_and_b32_e32 v215, 0xffff0000, v146
	v_lshlrev_b32_e32 v144, 16, v145
	v_and_b32_e32 v145, 0xffff0000, v145
	v_lshlrev_b32_e32 v146, 16, v147
	v_and_b32_e32 v147, 0xffff0000, v147
	v_rcp_f32_e32 v212, v212
	v_rcp_f32_e32 v213, v213
	v_rcp_f32_e32 v144, v144
	v_rcp_f32_e32 v145, v145
	v_rcp_f32_e32 v214, v214
	v_rcp_f32_e32 v215, v215
	v_rcp_f32_e32 v146, v146
	v_rcp_f32_e32 v147, v147
	s_nop 0
	v_pk_mul_f32 v[148:149], v[148:149], v[212:213]
	v_pk_mul_f32 v[206:207], v[206:207], v[144:145]
	v_pk_mul_f32 v[210:211], v[210:211], v[214:215]
	v_pk_mul_f32 v[208:209], v[208:209], v[146:147]
	v_pk_mul_f32 v[70:71], v[70:71], v[148:149]
	v_pk_mul_f32 v[72:73], v[72:73], v[206:207]
	v_pk_mul_f32 v[66:67], v[66:67], v[210:211]
	v_pk_mul_f32 v[68:69], v[68:69], v[208:209]
	global_load_dwordx4 v[202:205], v140, s[24:25]
	global_load_dwordx4 v[206:209], v140, s[24:25] offset:2048
	s_waitcnt vmcnt(12)
	v_lshlrev_b32_e32 v148, 16, v154
	v_and_b32_e32 v149, 0xffff0000, v154
	v_lshlrev_b32_e32 v210, 16, v156
	v_and_b32_e32 v211, 0xffff0000, v156
	v_lshlrev_b32_e32 v154, 16, v155
	v_and_b32_e32 v155, 0xffff0000, v155
	v_lshlrev_b32_e32 v156, 16, v157
	v_and_b32_e32 v157, 0xffff0000, v157
	v_lshlrev_b32_e32 v212, 16, v158
	v_and_b32_e32 v213, 0xffff0000, v158
	v_lshlrev_b32_e32 v214, 16, v160
	v_and_b32_e32 v215, 0xffff0000, v160
	v_lshlrev_b32_e32 v158, 16, v159
	v_and_b32_e32 v159, 0xffff0000, v159
	v_lshlrev_b32_e32 v160, 16, v161
	v_and_b32_e32 v161, 0xffff0000, v161
	v_rcp_f32_e32 v212, v212
	v_rcp_f32_e32 v213, v213
	v_rcp_f32_e32 v158, v158
	v_rcp_f32_e32 v159, v159
	v_rcp_f32_e32 v214, v214
	v_rcp_f32_e32 v215, v215
	v_rcp_f32_e32 v160, v160
	v_rcp_f32_e32 v161, v161
	s_nop 0
	v_pk_mul_f32 v[148:149], v[148:149], v[212:213]
	v_pk_mul_f32 v[154:155], v[154:155], v[158:159]
	v_pk_mul_f32 v[210:211], v[210:211], v[214:215]
	v_pk_mul_f32 v[156:157], v[156:157], v[160:161]
	v_pk_mul_f32 v[62:63], v[62:63], v[148:149]
	v_pk_mul_f32 v[64:65], v[64:65], v[154:155]
	v_pk_mul_f32 v[58:59], v[58:59], v[210:211]
	v_pk_mul_f32 v[60:61], v[60:61], v[156:157]
	global_load_dwordx4 v[144:147], v140, s[24:25] offset:256
	global_load_dwordx4 v[154:157], v140, s[24:25] offset:2304
	s_waitcnt vmcnt(12)
; __device__ __forceinline__ float bf_lo(unsigned w) { return __uint_as_float(w << 16); }
; __device__ __forceinline__ float bf_hi(unsigned w) { return __uint_as_float(w & 0xffff0000u); }
;     __device__ __forceinline__ void operator()(ACC_T, const Unit& u, int wr, int wc, int fr, int fq) const {
;     ...
;             for (int m = 0; m < 4; ++m) { const size_t row = (size_t)(row0 + ai * HALF + m * 16);
; #pragma unroll
;                 for (int bj = 0; bj < 2; ++bj) {
;                     const u32x4 gw = *(const u32x4*)(Gt + row * GW + u.z * DM + col0 + bj * HALF);
;                     f32x4 v0 = acc[ai][bj][m][0], v1 = acc[ai][bj][m][1];
;                     v0[0] *= bf_lo(gw.x); v0[1] *= bf_hi(gw.x); v0[2] *= bf_lo(gw.y); v0[3] *= bf_hi(gw.y);
;                     v1[0] *= bf_lo(gw.z); v1[1] *= bf_hi(gw.z); v1[2] *= bf_lo(gw.w); v1[3] *= bf_hi(gw.w);
	v_lshlrev_b32_e32 v148, 16, v162
	v_and_b32_e32 v149, 0xffff0000, v162
	v_lshlrev_b32_e32 v210, 16, v164
	v_and_b32_e32 v211, 0xffff0000, v164
	v_lshlrev_b32_e32 v162, 16, v163
	v_and_b32_e32 v163, 0xffff0000, v163
	v_lshlrev_b32_e32 v164, 16, v165
	v_and_b32_e32 v165, 0xffff0000, v165
	v_lshlrev_b32_e32 v212, 16, v166
	v_and_b32_e32 v213, 0xffff0000, v166
	v_lshlrev_b32_e32 v214, 16, v168
	v_and_b32_e32 v215, 0xffff0000, v168
	v_lshlrev_b32_e32 v166, 16, v167
	v_and_b32_e32 v167, 0xffff0000, v167
	v_lshlrev_b32_e32 v168, 16, v169
	v_and_b32_e32 v169, 0xffff0000, v169
	v_rcp_f32_e32 v212, v212
	v_rcp_f32_e32 v213, v213
	v_rcp_f32_e32 v166, v166
	v_rcp_f32_e32 v167, v167
	v_rcp_f32_e32 v214, v214
	v_rcp_f32_e32 v215, v215
	v_rcp_f32_e32 v168, v168
	v_rcp_f32_e32 v169, v169
	s_nop 0
	v_pk_mul_f32 v[148:149], v[148:149], v[212:213]
	v_pk_mul_f32 v[162:163], v[162:163], v[166:167]
	v_pk_mul_f32 v[210:211], v[210:211], v[214:215]
	v_pk_mul_f32 v[164:165], v[164:165], v[168:169]
	v_pk_mul_f32 v[54:55], v[54:55], v[148:149]
	v_pk_mul_f32 v[56:57], v[56:57], v[162:163]
	v_pk_mul_f32 v[50:51], v[50:51], v[210:211]
	v_pk_mul_f32 v[52:53], v[52:53], v[164:165]
	s_waitcnt vmcnt(10)
	v_lshlrev_b32_e32 v148, 16, v170
	v_and_b32_e32 v149, 0xffff0000, v170
	v_lshlrev_b32_e32 v210, 16, v172
	v_and_b32_e32 v211, 0xffff0000, v172
	v_lshlrev_b32_e32 v170, 16, v171
	v_and_b32_e32 v171, 0xffff0000, v171
	v_lshlrev_b32_e32 v172, 16, v173
	v_and_b32_e32 v173, 0xffff0000, v173
	v_lshlrev_b32_e32 v212, 16, v174
	v_and_b32_e32 v213, 0xffff0000, v174
	v_lshlrev_b32_e32 v214, 16, v176
	v_and_b32_e32 v215, 0xffff0000, v176
	v_lshlrev_b32_e32 v174, 16, v175
	v_and_b32_e32 v175, 0xffff0000, v175
	v_lshlrev_b32_e32 v176, 16, v177
	v_and_b32_e32 v177, 0xffff0000, v177
	v_rcp_f32_e32 v212, v212
	v_rcp_f32_e32 v213, v213
	v_rcp_f32_e32 v174, v174
	v_rcp_f32_e32 v175, v175
	v_rcp_f32_e32 v214, v214
	v_rcp_f32_e32 v215, v215
	v_rcp_f32_e32 v176, v176
	v_rcp_f32_e32 v177, v177
	s_nop 0
	v_pk_mul_f32 v[148:149], v[148:149], v[212:213]
	v_pk_mul_f32 v[170:171], v[170:171], v[174:175]
	v_pk_mul_f32 v[210:211], v[210:211], v[214:215]
	v_pk_mul_f32 v[172:173], v[172:173], v[176:177]
	v_pk_mul_f32 v[46:47], v[46:47], v[148:149]
	v_pk_mul_f32 v[48:49], v[48:49], v[170:171]
	v_pk_mul_f32 v[42:43], v[42:43], v[210:211]
	v_pk_mul_f32 v[44:45], v[44:45], v[172:173]
	s_waitcnt vmcnt(8)
	v_lshlrev_b32_e32 v148, 16, v178
	v_and_b32_e32 v149, 0xffff0000, v178
	v_lshlrev_b32_e32 v210, 16, v180
	v_and_b32_e32 v211, 0xffff0000, v180
	v_lshlrev_b32_e32 v178, 16, v179
	v_and_b32_e32 v179, 0xffff0000, v179
	v_lshlrev_b32_e32 v180, 16, v181
	v_and_b32_e32 v181, 0xffff0000, v181
	v_lshlrev_b32_e32 v212, 16, v182
	v_and_b32_e32 v213, 0xffff0000, v182
	v_lshlrev_b32_e32 v214, 16, v184
	v_and_b32_e32 v215, 0xffff0000, v184
	v_lshlrev_b32_e32 v182, 16, v183
	v_and_b32_e32 v183, 0xffff0000, v183
	v_lshlrev_b32_e32 v184, 16, v185
	v_and_b32_e32 v185, 0xffff0000, v185
	v_rcp_f32_e32 v212, v212
	v_rcp_f32_e32 v213, v213
	v_rcp_f32_e32 v182, v182
	v_rcp_f32_e32 v183, v183
	v_rcp_f32_e32 v214, v214
	v_rcp_f32_e32 v215, v215
	v_rcp_f32_e32 v184, v184
	v_rcp_f32_e32 v185, v185
	s_nop 0
	v_pk_mul_f32 v[148:149], v[148:149], v[212:213]
	v_pk_mul_f32 v[178:179], v[178:179], v[182:183]
	v_pk_mul_f32 v[210:211], v[210:211], v[214:215]
	v_pk_mul_f32 v[180:181], v[180:181], v[184:185]
	v_pk_mul_f32 v[38:39], v[38:39], v[148:149]
	v_pk_mul_f32 v[40:41], v[40:41], v[178:179]
	v_pk_mul_f32 v[34:35], v[34:35], v[210:211]
	v_pk_mul_f32 v[36:37], v[36:37], v[180:181]
	s_waitcnt vmcnt(6)
	v_lshlrev_b32_e32 v148, 16, v186
	v_and_b32_e32 v149, 0xffff0000, v186
	v_lshlrev_b32_e32 v210, 16, v188
	v_and_b32_e32 v211, 0xffff0000, v188
	v_lshlrev_b32_e32 v186, 16, v187
	v_and_b32_e32 v187, 0xffff0000, v187
	v_lshlrev_b32_e32 v188, 16, v189
	v_and_b32_e32 v189, 0xffff0000, v189
	v_lshlrev_b32_e32 v212, 16, v190
	v_and_b32_e32 v213, 0xffff0000, v190
	v_lshlrev_b32_e32 v214, 16, v192
	v_and_b32_e32 v215, 0xffff0000, v192
	v_lshlrev_b32_e32 v190, 16, v191
	v_and_b32_e32 v191, 0xffff0000, v191
	v_lshlrev_b32_e32 v192, 16, v193
	v_and_b32_e32 v193, 0xffff0000, v193
	v_rcp_f32_e32 v212, v212
	v_rcp_f32_e32 v213, v213
	v_rcp_f32_e32 v190, v190
	v_rcp_f32_e32 v191, v191
	v_rcp_f32_e32 v214, v214
	v_rcp_f32_e32 v215, v215
	v_rcp_f32_e32 v192, v192
	v_rcp_f32_e32 v193, v193
	s_nop 0
	v_pk_mul_f32 v[148:149], v[148:149], v[212:213]
	v_pk_mul_f32 v[186:187], v[186:187], v[190:191]
	v_pk_mul_f32 v[210:211], v[210:211], v[214:215]
	v_pk_mul_f32 v[188:189], v[188:189], v[192:193]
	v_pk_mul_f32 v[30:31], v[30:31], v[148:149]
	v_pk_mul_f32 v[32:33], v[32:33], v[186:187]
	v_pk_mul_f32 v[26:27], v[26:27], v[210:211]
	v_pk_mul_f32 v[28:29], v[28:29], v[188:189]
	s_waitcnt vmcnt(4)
	v_lshlrev_b32_e32 v148, 16, v194
	v_and_b32_e32 v149, 0xffff0000, v194
	v_lshlrev_b32_e32 v210, 16, v196
	v_and_b32_e32 v211, 0xffff0000, v196
	v_lshlrev_b32_e32 v194, 16, v195
	v_and_b32_e32 v195, 0xffff0000, v195
	v_lshlrev_b32_e32 v196, 16, v197
	v_and_b32_e32 v197, 0xffff0000, v197
	v_lshlrev_b32_e32 v212, 16, v198
	v_and_b32_e32 v213, 0xffff0000, v198
	v_lshlrev_b32_e32 v214, 16, v200
	v_and_b32_e32 v215, 0xffff0000, v200
	v_lshlrev_b32_e32 v198, 16, v199
	v_and_b32_e32 v199, 0xffff0000, v199
	v_lshlrev_b32_e32 v200, 16, v201
	v_and_b32_e32 v201, 0xffff0000, v201
	v_rcp_f32_e32 v212, v212
	v_rcp_f32_e32 v213, v213
	v_rcp_f32_e32 v198, v198
	v_rcp_f32_e32 v199, v199
	v_rcp_f32_e32 v214, v214
	v_rcp_f32_e32 v215, v215
	v_rcp_f32_e32 v200, v200
	v_rcp_f32_e32 v201, v201
	s_nop 0
	v_pk_mul_f32 v[148:149], v[148:149], v[212:213]
	v_pk_mul_f32 v[194:195], v[194:195], v[198:199]
	v_pk_mul_f32 v[210:211], v[210:211], v[214:215]
	v_pk_mul_f32 v[196:197], v[196:197], v[200:201]
	v_pk_mul_f32 v[22:23], v[22:23], v[148:149]
	v_pk_mul_f32 v[24:25], v[24:25], v[194:195]
	v_pk_mul_f32 v[18:19], v[18:19], v[210:211]
	v_pk_mul_f32 v[20:21], v[20:21], v[196:197]
	s_waitcnt vmcnt(2)
; __device__ __forceinline__ unsigned cvt_pk_bf16(float lo, float hi) { f32x2 v = {lo, hi}; bf16x2_t b = __builtin_convertvector(v, bf16x2_t); return __builtin_bit_cast(unsigned, b); }
; __device__ __forceinline__ float bf_lo(unsigned w) { return __uint_as_float(w << 16); }
; __device__ __forceinline__ float bf_hi(unsigned w) { return __uint_as_float(w & 0xffff0000u); }
;     __device__ __forceinline__ void operator()(ACC_T, const Unit& u, int wr, int wc, int fr, int fq) const {
;     ...
;             for (int m = 0; m < 4; ++m) { const size_t row = (size_t)(row0 + ai * HALF + m * 16);
; #pragma unroll
;                 for (int bj = 0; bj < 2; ++bj) {
;                     const u32x4 gw = *(const u32x4*)(Gt + row * GW + u.z * DM + col0 + bj * HALF);
;                     f32x4 v0 = acc[ai][bj][m][0], v1 = acc[ai][bj][m][1];
;                     v0[0] *= bf_lo(gw.x); v0[1] *= bf_hi(gw.x); v0[2] *= bf_lo(gw.y); v0[3] *= bf_hi(gw.y);
;                     v1[0] *= bf_lo(gw.z); v1[1] *= bf_hi(gw.z); v1[2] *= bf_lo(gw.w); v1[3] *= bf_hi(gw.w);
;                     float* mp = M32 + (size_t)u.pm * (SLOTB / 4) + (row - (size_t)u.pm * BM) * DM + col0 + bj * HALF;
;                     if (u.z > 0) { v0 += *(const f32x4*)mp; v1 += *(const f32x4*)(mp + 4); }
;                     if (u.z < 2) { *(f32x4*)mp = v0; *(f32x4*)(mp + 4) = v1; }
;                     else { u32x4 w; w.x = cvt_pk_bf16(v0[0], v0[1]); w.y = cvt_pk_bf16(v0[2], v0[3]); w.z = cvt_pk_bf16(v1[0], v1[1]); w.w = cvt_pk_bf16(v1[2], v1[3]);
;                         *(u32x4*)(MG + row * DM + col0 + bj * HALF) = w; } } }
	v_lshlrev_b32_e32 v148, 16, v202
	v_and_b32_e32 v149, 0xffff0000, v202
	v_lshlrev_b32_e32 v210, 16, v204
	v_and_b32_e32 v211, 0xffff0000, v204
	v_lshlrev_b32_e32 v202, 16, v203
	v_and_b32_e32 v203, 0xffff0000, v203
	v_lshlrev_b32_e32 v204, 16, v205
	v_and_b32_e32 v205, 0xffff0000, v205
	v_lshlrev_b32_e32 v212, 16, v206
	v_and_b32_e32 v213, 0xffff0000, v206
	v_lshlrev_b32_e32 v214, 16, v208
	v_and_b32_e32 v215, 0xffff0000, v208
	v_lshlrev_b32_e32 v206, 16, v207
	v_and_b32_e32 v207, 0xffff0000, v207
	v_lshlrev_b32_e32 v208, 16, v209
	v_and_b32_e32 v209, 0xffff0000, v209
	v_rcp_f32_e32 v212, v212
	v_rcp_f32_e32 v213, v213
	v_rcp_f32_e32 v206, v206
	v_rcp_f32_e32 v207, v207
	v_rcp_f32_e32 v214, v214
	v_rcp_f32_e32 v215, v215
	v_rcp_f32_e32 v208, v208
	v_rcp_f32_e32 v209, v209
	s_nop 0
	v_pk_mul_f32 v[148:149], v[148:149], v[212:213]
	v_pk_mul_f32 v[202:203], v[202:203], v[206:207]
	v_pk_mul_f32 v[210:211], v[210:211], v[214:215]
	v_pk_mul_f32 v[204:205], v[204:205], v[208:209]
	v_pk_mul_f32 v[14:15], v[14:15], v[148:149]
	v_pk_mul_f32 v[16:17], v[16:17], v[202:203]
	v_pk_mul_f32 v[10:11], v[10:11], v[210:211]
	v_pk_mul_f32 v[12:13], v[12:13], v[204:205]
	s_waitcnt vmcnt(0)
	v_lshlrev_b32_e32 v148, 16, v144
	v_and_b32_e32 v149, 0xffff0000, v144
	v_lshlrev_b32_e32 v210, 16, v146
	v_and_b32_e32 v211, 0xffff0000, v146
	v_lshlrev_b32_e32 v144, 16, v145
	v_and_b32_e32 v145, 0xffff0000, v145
	v_lshlrev_b32_e32 v146, 16, v147
	v_and_b32_e32 v147, 0xffff0000, v147
	v_lshlrev_b32_e32 v212, 16, v154
	v_and_b32_e32 v213, 0xffff0000, v154
	v_lshlrev_b32_e32 v214, 16, v156
	v_and_b32_e32 v215, 0xffff0000, v156
	v_lshlrev_b32_e32 v154, 16, v155
	v_and_b32_e32 v155, 0xffff0000, v155
	v_lshlrev_b32_e32 v156, 16, v157
	v_and_b32_e32 v157, 0xffff0000, v157
	v_rcp_f32_e32 v212, v212
	v_rcp_f32_e32 v213, v213
	v_rcp_f32_e32 v154, v154
	v_rcp_f32_e32 v155, v155
	v_rcp_f32_e32 v214, v214
	v_rcp_f32_e32 v215, v215
	v_rcp_f32_e32 v156, v156
	v_rcp_f32_e32 v157, v157
	s_nop 0
	v_pk_mul_f32 v[148:149], v[148:149], v[212:213]
	v_pk_mul_f32 v[144:145], v[144:145], v[154:155]
	v_pk_mul_f32 v[210:211], v[210:211], v[214:215]
	v_pk_mul_f32 v[146:147], v[146:147], v[156:157]
	v_pk_mul_f32 v[6:7], v[6:7], v[148:149]
	v_pk_mul_f32 v[8:9], v[8:9], v[144:145]
	v_pk_mul_f32 v[2:3], v[2:3], v[210:211]
	v_pk_mul_f32 v[4:5], v[4:5], v[146:147]
	s_branch .Lbr_done
.Lbr_zlast:
	global_load_dwordx4 v[144:147], v140, s[24:25]
	global_load_dwordx4 v[154:157], v140, s[24:25] offset:256
	s_add_u32 s24, s24, 0x18000
	s_addc_u32 s25, s25, 0
	global_load_dwordx4 v[158:161], v140, s[24:25]
	global_load_dwordx4 v[162:165], v140, s[24:25] offset:256
	s_add_u32 s24, s24, 0x18000
	s_addc_u32 s25, s25, 0
	global_load_dwordx4 v[166:169], v140, s[24:25]
	global_load_dwordx4 v[170:173], v140, s[24:25] offset:256
	s_add_u32 s24, s24, 0x18000
	s_addc_u32 s25, s25, 0
	global_load_dwordx4 v[174:177], v140, s[24:25]
	global_load_dwordx4 v[178:181], v140, s[24:25] offset:256
	s_add_u32 s24, s24, 0x78000
	s_addc_u32 s25, s25, 0
	global_load_dwordx4 v[182:185], v140, s[24:25]
	global_load_dwordx4 v[186:189], v140, s[24:25] offset:256
	s_add_u32 s24, s24, 0x18000
	s_addc_u32 s25, s25, 0
	global_load_dwordx4 v[190:193], v140, s[24:25]
	global_load_dwordx4 v[194:197], v140, s[24:25] offset:256
	s_add_u32 s24, s24, 0x18000
	s_addc_u32 s25, s25, 0
	global_load_dwordx4 v[198:201], v140, s[24:25]
	s_waitcnt vmcnt(12)
	v_lshlrev_b32_e32 v148, 16, v144
	v_and_b32_e32 v149, 0xffff0000, v144
	v_lshlrev_b32_e32 v210, 16, v146
	v_and_b32_e32 v211, 0xffff0000, v146
	v_lshlrev_b32_e32 v144, 16, v145
	v_and_b32_e32 v145, 0xffff0000, v145
	v_lshlrev_b32_e32 v146, 16, v147
	v_and_b32_e32 v147, 0xffff0000, v147
	v_pk_mul_f32 v[126:127], v[126:127], v[148:149]
	v_pk_mul_f32 v[128:129], v[128:129], v[144:145]
	v_pk_mul_f32 v[122:123], v[122:123], v[210:211]
	v_pk_mul_f32 v[124:125], v[124:125], v[146:147]
	v_cvt_pk_bf16_f32 v144, v126, v127
	v_cvt_pk_bf16_f32 v145, v128, v129
	v_cvt_pk_bf16_f32 v146, v122, v123
	v_cvt_pk_bf16_f32 v147, v124, v125
	global_store_dwordx4 v142, v[144:147], s[22:23]
	global_load_dwordx4 v[202:205], v140, s[24:25] offset:256
	s_add_u32 s24, s24, 0x18000
	s_addc_u32 s25, s25, 0
	s_waitcnt vmcnt(13)
	v_lshlrev_b32_e32 v148, 16, v154
	v_and_b32_e32 v149, 0xffff0000, v154
	v_lshlrev_b32_e32 v210, 16, v156
	v_and_b32_e32 v211, 0xffff0000, v156
	v_lshlrev_b32_e32 v154, 16, v155
	v_and_b32_e32 v155, 0xffff0000, v155
	v_lshlrev_b32_e32 v156, 16, v157
	v_and_b32_e32 v157, 0xffff0000, v157
	v_pk_mul_f32 v[118:119], v[118:119], v[148:149]
	v_pk_mul_f32 v[120:121], v[120:121], v[154:155]
	v_pk_mul_f32 v[114:115], v[114:115], v[210:211]
	v_pk_mul_f32 v[116:117], v[116:117], v[156:157]
	v_cvt_pk_bf16_f32 v154, v118, v119
	v_cvt_pk_bf16_f32 v155, v120, v121
	v_cvt_pk_bf16_f32 v156, v114, v115
	v_cvt_pk_bf16_f32 v157, v116, v117
	global_store_dwordx4 v142, v[154:157], s[22:23] offset:256
	s_add_u32 s22, s22, 0x8000
	s_addc_u32 s23, s23, 0
	global_load_dwordx4 v[206:209], v140, s[24:25]
	s_waitcnt vmcnt(14)
	v_lshlrev_b32_e32 v148, 16, v158
	v_and_b32_e32 v149, 0xffff0000, v158
	v_lshlrev_b32_e32 v210, 16, v160
	v_and_b32_e32 v211, 0xffff0000, v160
	v_lshlrev_b32_e32 v158, 16, v159
	v_and_b32_e32 v159, 0xffff0000, v159
	v_lshlrev_b32_e32 v160, 16, v161
	v_and_b32_e32 v161, 0xffff0000, v161
	v_pk_mul_f32 v[110:111], v[110:111], v[148:149]
	v_pk_mul_f32 v[112:113], v[112:113], v[158:159]
	v_pk_mul_f32 v[106:107], v[106:107], v[210:211]
	v_pk_mul_f32 v[108:109], v[108:109], v[160:161]
	v_cvt_pk_bf16_f32 v158, v110, v111
	v_cvt_pk_bf16_f32 v159, v112, v113
	v_cvt_pk_bf16_f32 v160, v106, v107
	v_cvt_pk_bf16_f32 v161, v108, v109
	global_store_dwordx4 v142, v[158:161], s[22:23]
	global_load_dwordx4 v[126:129], v140, s[24:25] offset:256
	s_waitcnt vmcnt(15)
; __device__ __forceinline__ unsigned cvt_pk_bf16(float lo, float hi) { f32x2 v = {lo, hi}; bf16x2_t b = __builtin_convertvector(v, bf16x2_t); return __builtin_bit_cast(unsigned, b); }
; __device__ __forceinline__ float bf_lo(unsigned w) { return __uint_as_float(w << 16); }
; __device__ __forceinline__ float bf_hi(unsigned w) { return __uint_as_float(w & 0xffff0000u); }
;     __device__ __forceinline__ void operator()(ACC_T, const Unit& u, int wr, int wc, int fr, int fq) const {
;     ...
;             for (int m = 0; m < 4; ++m) { const size_t row = (size_t)(row0 + ai * HALF + m * 16);
; #pragma unroll
;                 for (int bj = 0; bj < 2; ++bj) {
;                     const u32x4 gw = *(const u32x4*)(Gt + row * GW + u.z * DM + col0 + bj * HALF);
;                     f32x4 v0 = acc[ai][bj][m][0], v1 = acc[ai][bj][m][1];
;                     v0[0] *= bf_lo(gw.x); v0[1] *= bf_hi(gw.x); v0[2] *= bf_lo(gw.y); v0[3] *= bf_hi(gw.y);
;                     v1[0] *= bf_lo(gw.z); v1[1] *= bf_hi(gw.z); v1[2] *= bf_lo(gw.w); v1[3] *= bf_hi(gw.w);
;                     float* mp = M32 + (size_t)u.pm * (SLOTB / 4) + (row - (size_t)u.pm * BM) * DM + col0 + bj * HALF;
;                     if (u.z > 0) { v0 += *(const f32x4*)mp; v1 += *(const f32x4*)(mp + 4); }
;                     if (u.z < 2) { *(f32x4*)mp = v0; *(f32x4*)(mp + 4) = v1; }
;                     else { u32x4 w; w.x = cvt_pk_bf16(v0[0], v0[1]); w.y = cvt_pk_bf16(v0[2], v0[3]); w.z = cvt_pk_bf16(v1[0], v1[1]); w.w = cvt_pk_bf16(v1[2], v1[3]);
;                         *(u32x4*)(MG + row * DM + col0 + bj * HALF) = w; } } }
	v_lshlrev_b32_e32 v148, 16, v162
	v_and_b32_e32 v149, 0xffff0000, v162
	v_lshlrev_b32_e32 v210, 16, v164
	v_and_b32_e32 v211, 0xffff0000, v164
	v_lshlrev_b32_e32 v162, 16, v163
	v_and_b32_e32 v163, 0xffff0000, v163
	v_lshlrev_b32_e32 v164, 16, v165
	v_and_b32_e32 v165, 0xffff0000, v165
	v_pk_mul_f32 v[102:103], v[102:103], v[148:149]
	v_pk_mul_f32 v[104:105], v[104:105], v[162:163]
	v_pk_mul_f32 v[98:99], v[98:99], v[210:211]
	v_pk_mul_f32 v[100:101], v[100:101], v[164:165]
	v_cvt_pk_bf16_f32 v162, v102, v103
	v_cvt_pk_bf16_f32 v163, v104, v105
	v_cvt_pk_bf16_f32 v164, v98, v99
	v_cvt_pk_bf16_f32 v165, v100, v101
	global_store_dwordx4 v142, v[162:165], s[22:23] offset:256
	s_add_u32 s22, s22, 0x8000
	s_addc_u32 s23, s23, 0
	s_waitcnt vmcnt(15)
	v_lshlrev_b32_e32 v148, 16, v166
	v_and_b32_e32 v149, 0xffff0000, v166
	v_lshlrev_b32_e32 v210, 16, v168
	v_and_b32_e32 v211, 0xffff0000, v168
	v_lshlrev_b32_e32 v166, 16, v167
	v_and_b32_e32 v167, 0xffff0000, v167
	v_lshlrev_b32_e32 v168, 16, v169
	v_and_b32_e32 v169, 0xffff0000, v169
	v_pk_mul_f32 v[94:95], v[94:95], v[148:149]
	v_pk_mul_f32 v[96:97], v[96:97], v[166:167]
	v_pk_mul_f32 v[90:91], v[90:91], v[210:211]
	v_pk_mul_f32 v[92:93], v[92:93], v[168:169]
	v_cvt_pk_bf16_f32 v166, v94, v95
	v_cvt_pk_bf16_f32 v167, v96, v97
	v_cvt_pk_bf16_f32 v168, v90, v91
	v_cvt_pk_bf16_f32 v169, v92, v93
	global_store_dwordx4 v142, v[166:169], s[22:23]
	s_waitcnt vmcnt(15)
	v_lshlrev_b32_e32 v148, 16, v170
	v_and_b32_e32 v149, 0xffff0000, v170
	v_lshlrev_b32_e32 v210, 16, v172
	v_and_b32_e32 v211, 0xffff0000, v172
	v_lshlrev_b32_e32 v170, 16, v171
	v_and_b32_e32 v171, 0xffff0000, v171
	v_lshlrev_b32_e32 v172, 16, v173
	v_and_b32_e32 v173, 0xffff0000, v173
	v_pk_mul_f32 v[86:87], v[86:87], v[148:149]
	v_pk_mul_f32 v[88:89], v[88:89], v[170:171]
	v_pk_mul_f32 v[82:83], v[82:83], v[210:211]
	v_pk_mul_f32 v[84:85], v[84:85], v[172:173]
	v_cvt_pk_bf16_f32 v170, v86, v87
	v_cvt_pk_bf16_f32 v171, v88, v89
	v_cvt_pk_bf16_f32 v172, v82, v83
	v_cvt_pk_bf16_f32 v173, v84, v85
	global_store_dwordx4 v142, v[170:173], s[22:23] offset:256
	s_add_u32 s22, s22, 0x8000
	s_addc_u32 s23, s23, 0
	s_waitcnt vmcnt(15)
	v_lshlrev_b32_e32 v148, 16, v174
	v_and_b32_e32 v149, 0xffff0000, v174
	v_lshlrev_b32_e32 v210, 16, v176
	v_and_b32_e32 v211, 0xffff0000, v176
	v_lshlrev_b32_e32 v174, 16, v175
	v_and_b32_e32 v175, 0xffff0000, v175
	v_lshlrev_b32_e32 v176, 16, v177
	v_and_b32_e32 v177, 0xffff0000, v177
	v_pk_mul_f32 v[78:79], v[78:79], v[148:149]
	v_pk_mul_f32 v[80:81], v[80:81], v[174:175]
	v_pk_mul_f32 v[74:75], v[74:75], v[210:211]
	v_pk_mul_f32 v[76:77], v[76:77], v[176:177]
	v_cvt_pk_bf16_f32 v174, v78, v79
	v_cvt_pk_bf16_f32 v175, v80, v81
	v_cvt_pk_bf16_f32 v176, v74, v75
	v_cvt_pk_bf16_f32 v177, v76, v77
	global_store_dwordx4 v142, v[174:177], s[22:23]
	s_waitcnt vmcnt(15)
	v_lshlrev_b32_e32 v148, 16, v178
	v_and_b32_e32 v149, 0xffff0000, v178
	v_lshlrev_b32_e32 v210, 16, v180
	v_and_b32_e32 v211, 0xffff0000, v180
	v_lshlrev_b32_e32 v178, 16, v179
	v_and_b32_e32 v179, 0xffff0000, v179
	v_lshlrev_b32_e32 v180, 16, v181
	v_and_b32_e32 v181, 0xffff0000, v181
	v_pk_mul_f32 v[70:71], v[70:71], v[148:149]
	v_pk_mul_f32 v[72:73], v[72:73], v[178:179]
	v_pk_mul_f32 v[66:67], v[66:67], v[210:211]
	v_pk_mul_f32 v[68:69], v[68:69], v[180:181]
	v_cvt_pk_bf16_f32 v178, v70, v71
	v_cvt_pk_bf16_f32 v179, v72, v73
	v_cvt_pk_bf16_f32 v180, v66, v67
	v_cvt_pk_bf16_f32 v181, v68, v69
	global_store_dwordx4 v142, v[178:181], s[22:23] offset:256
	s_add_u32 s22, s22, 0x28000
	s_addc_u32 s23, s23, 0
	s_waitcnt vmcnt(15)
	v_lshlrev_b32_e32 v148, 16, v182
	v_and_b32_e32 v149, 0xffff0000, v182
	v_lshlrev_b32_e32 v210, 16, v184
	v_and_b32_e32 v211, 0xffff0000, v184
	v_lshlrev_b32_e32 v182, 16, v183
	v_and_b32_e32 v183, 0xffff0000, v183
	v_lshlrev_b32_e32 v184, 16, v185
	v_and_b32_e32 v185, 0xffff0000, v185
	v_pk_mul_f32 v[62:63], v[62:63], v[148:149]
	v_pk_mul_f32 v[64:65], v[64:65], v[182:183]
	v_pk_mul_f32 v[58:59], v[58:59], v[210:211]
	v_pk_mul_f32 v[60:61], v[60:61], v[184:185]
	v_cvt_pk_bf16_f32 v182, v62, v63
	v_cvt_pk_bf16_f32 v183, v64, v65
	v_cvt_pk_bf16_f32 v184, v58, v59
	v_cvt_pk_bf16_f32 v185, v60, v61
	global_store_dwordx4 v142, v[182:185], s[22:23]
	s_waitcnt vmcnt(15)
; __device__ __forceinline__ unsigned cvt_pk_bf16(float lo, float hi) { f32x2 v = {lo, hi}; bf16x2_t b = __builtin_convertvector(v, bf16x2_t); return __builtin_bit_cast(unsigned, b); }
; __device__ __forceinline__ float bf_lo(unsigned w) { return __uint_as_float(w << 16); }
; __device__ __forceinline__ float bf_hi(unsigned w) { return __uint_as_float(w & 0xffff0000u); }
;     __device__ __forceinline__ void operator()(ACC_T, const Unit& u, int wr, int wc, int fr, int fq) const {
;     ...
;             for (int m = 0; m < 4; ++m) { const size_t row = (size_t)(row0 + ai * HALF + m * 16);
; #pragma unroll
;                 for (int bj = 0; bj < 2; ++bj) {
;                     const u32x4 gw = *(const u32x4*)(Gt + row * GW + u.z * DM + col0 + bj * HALF);
;                     f32x4 v0 = acc[ai][bj][m][0], v1 = acc[ai][bj][m][1];
;                     v0[0] *= bf_lo(gw.x); v0[1] *= bf_hi(gw.x); v0[2] *= bf_lo(gw.y); v0[3] *= bf_hi(gw.y);
;                     v1[0] *= bf_lo(gw.z); v1[1] *= bf_hi(gw.z); v1[2] *= bf_lo(gw.w); v1[3] *= bf_hi(gw.w);
;                     float* mp = M32 + (size_t)u.pm * (SLOTB / 4) + (row - (size_t)u.pm * BM) * DM + col0 + bj * HALF;
;                     if (u.z > 0) { v0 += *(const f32x4*)mp; v1 += *(const f32x4*)(mp + 4); }
;                     if (u.z < 2) { *(f32x4*)mp = v0; *(f32x4*)(mp + 4) = v1; }
;                     else { u32x4 w; w.x = cvt_pk_bf16(v0[0], v0[1]); w.y = cvt_pk_bf16(v0[2], v0[3]); w.z = cvt_pk_bf16(v1[0], v1[1]); w.w = cvt_pk_bf16(v1[2], v1[3]);
;                         *(u32x4*)(MG + row * DM + col0 + bj * HALF) = w; } } }
	v_lshlrev_b32_e32 v148, 16, v186
	v_and_b32_e32 v149, 0xffff0000, v186
	v_lshlrev_b32_e32 v210, 16, v188
	v_and_b32_e32 v211, 0xffff0000, v188
	v_lshlrev_b32_e32 v186, 16, v187
	v_and_b32_e32 v187, 0xffff0000, v187
	v_lshlrev_b32_e32 v188, 16, v189
	v_and_b32_e32 v189, 0xffff0000, v189
	v_pk_mul_f32 v[54:55], v[54:55], v[148:149]
	v_pk_mul_f32 v[56:57], v[56:57], v[186:187]
	v_pk_mul_f32 v[50:51], v[50:51], v[210:211]
	v_pk_mul_f32 v[52:53], v[52:53], v[188:189]
	v_cvt_pk_bf16_f32 v186, v54, v55
	v_cvt_pk_bf16_f32 v187, v56, v57
	v_cvt_pk_bf16_f32 v188, v50, v51
	v_cvt_pk_bf16_f32 v189, v52, v53
	global_store_dwordx4 v142, v[186:189], s[22:23] offset:256
	s_add_u32 s22, s22, 0x8000
	s_addc_u32 s23, s23, 0
	s_waitcnt vmcnt(15)
	v_lshlrev_b32_e32 v148, 16, v190
	v_and_b32_e32 v149, 0xffff0000, v190
	v_lshlrev_b32_e32 v210, 16, v192
	v_and_b32_e32 v211, 0xffff0000, v192
	v_lshlrev_b32_e32 v190, 16, v191
	v_and_b32_e32 v191, 0xffff0000, v191
	v_lshlrev_b32_e32 v192, 16, v193
	v_and_b32_e32 v193, 0xffff0000, v193
	v_pk_mul_f32 v[46:47], v[46:47], v[148:149]
	v_pk_mul_f32 v[48:49], v[48:49], v[190:191]
	v_pk_mul_f32 v[42:43], v[42:43], v[210:211]
	v_pk_mul_f32 v[44:45], v[44:45], v[192:193]
	v_cvt_pk_bf16_f32 v190, v46, v47
	v_cvt_pk_bf16_f32 v191, v48, v49
	v_cvt_pk_bf16_f32 v192, v42, v43
	v_cvt_pk_bf16_f32 v193, v44, v45
	global_store_dwordx4 v142, v[190:193], s[22:23]
	s_waitcnt vmcnt(15)
	v_lshlrev_b32_e32 v148, 16, v194
	v_and_b32_e32 v149, 0xffff0000, v194
	v_lshlrev_b32_e32 v210, 16, v196
	v_and_b32_e32 v211, 0xffff0000, v196
	v_lshlrev_b32_e32 v194, 16, v195
	v_and_b32_e32 v195, 0xffff0000, v195
	v_lshlrev_b32_e32 v196, 16, v197
	v_and_b32_e32 v197, 0xffff0000, v197
	v_pk_mul_f32 v[38:39], v[38:39], v[148:149]
	v_pk_mul_f32 v[40:41], v[40:41], v[194:195]
	v_pk_mul_f32 v[34:35], v[34:35], v[210:211]
	v_pk_mul_f32 v[36:37], v[36:37], v[196:197]
	v_cvt_pk_bf16_f32 v194, v38, v39
	v_cvt_pk_bf16_f32 v195, v40, v41
	v_cvt_pk_bf16_f32 v196, v34, v35
	v_cvt_pk_bf16_f32 v197, v36, v37
	global_store_dwordx4 v142, v[194:197], s[22:23] offset:256
	s_add_u32 s22, s22, 0x8000
	s_addc_u32 s23, s23, 0
	s_waitcnt vmcnt(15)
	v_lshlrev_b32_e32 v148, 16, v198
	v_and_b32_e32 v149, 0xffff0000, v198
	v_lshlrev_b32_e32 v210, 16, v200
	v_and_b32_e32 v211, 0xffff0000, v200
	v_lshlrev_b32_e32 v198, 16, v199
	v_and_b32_e32 v199, 0xffff0000, v199
	v_lshlrev_b32_e32 v200, 16, v201
	v_and_b32_e32 v201, 0xffff0000, v201
	v_pk_mul_f32 v[30:31], v[30:31], v[148:149]
	v_pk_mul_f32 v[32:33], v[32:33], v[198:199]
	v_pk_mul_f32 v[26:27], v[26:27], v[210:211]
	v_pk_mul_f32 v[28:29], v[28:29], v[200:201]
	v_cvt_pk_bf16_f32 v198, v30, v31
	v_cvt_pk_bf16_f32 v199, v32, v33
	v_cvt_pk_bf16_f32 v200, v26, v27
	v_cvt_pk_bf16_f32 v201, v28, v29
	global_store_dwordx4 v142, v[198:201], s[22:23]
	s_waitcnt vmcnt(14)
	v_lshlrev_b32_e32 v148, 16, v202
	v_and_b32_e32 v149, 0xffff0000, v202
	v_lshlrev_b32_e32 v210, 16, v204
	v_and_b32_e32 v211, 0xffff0000, v204
	v_lshlrev_b32_e32 v202, 16, v203
	v_and_b32_e32 v203, 0xffff0000, v203
	v_lshlrev_b32_e32 v204, 16, v205
	v_and_b32_e32 v205, 0xffff0000, v205
	v_pk_mul_f32 v[22:23], v[22:23], v[148:149]
	v_pk_mul_f32 v[24:25], v[24:25], v[202:203]
	v_pk_mul_f32 v[18:19], v[18:19], v[210:211]
	v_pk_mul_f32 v[20:21], v[20:21], v[204:205]
	v_cvt_pk_bf16_f32 v202, v22, v23
	v_cvt_pk_bf16_f32 v203, v24, v25
	v_cvt_pk_bf16_f32 v204, v18, v19
	v_cvt_pk_bf16_f32 v205, v20, v21
	global_store_dwordx4 v142, v[202:205], s[22:23] offset:256
	s_add_u32 s22, s22, 0x8000
	s_addc_u32 s23, s23, 0
	s_waitcnt vmcnt(13)
	v_lshlrev_b32_e32 v148, 16, v206
	v_and_b32_e32 v149, 0xffff0000, v206
	v_lshlrev_b32_e32 v210, 16, v208
	v_and_b32_e32 v211, 0xffff0000, v208
	v_lshlrev_b32_e32 v206, 16, v207
	v_and_b32_e32 v207, 0xffff0000, v207
	v_lshlrev_b32_e32 v208, 16, v209
	v_and_b32_e32 v209, 0xffff0000, v209
	v_pk_mul_f32 v[14:15], v[14:15], v[148:149]
	v_pk_mul_f32 v[16:17], v[16:17], v[206:207]
	v_pk_mul_f32 v[10:11], v[10:11], v[210:211]
	v_pk_mul_f32 v[12:13], v[12:13], v[208:209]
	v_cvt_pk_bf16_f32 v206, v14, v15
	v_cvt_pk_bf16_f32 v207, v16, v17
	v_cvt_pk_bf16_f32 v208, v10, v11
	v_cvt_pk_bf16_f32 v209, v12, v13
	global_store_dwordx4 v142, v[206:209], s[22:23]
	s_waitcnt vmcnt(12)
	v_lshlrev_b32_e32 v148, 16, v126
	v_and_b32_e32 v149, 0xffff0000, v126
	v_lshlrev_b32_e32 v210, 16, v128
	v_and_b32_e32 v211, 0xffff0000, v128
	v_lshlrev_b32_e32 v126, 16, v127
	v_and_b32_e32 v127, 0xffff0000, v127
	v_lshlrev_b32_e32 v128, 16, v129
	v_and_b32_e32 v129, 0xffff0000, v129
	v_pk_mul_f32 v[6:7], v[6:7], v[148:149]
	v_pk_mul_f32 v[8:9], v[8:9], v[126:127]
	v_pk_mul_f32 v[2:3], v[2:3], v[210:211]
	v_pk_mul_f32 v[4:5], v[4:5], v[128:129]
	v_cvt_pk_bf16_f32 v126, v6, v7
	v_cvt_pk_bf16_f32 v127, v8, v9
	v_cvt_pk_bf16_f32 v128, v2, v3
	v_cvt_pk_bf16_f32 v129, v4, v5
	global_store_dwordx4 v142, v[126:129], s[22:23] offset:256
